# GEMM G1/G2/P9: per-phase s_setprio flips deleted, one static s_setprio 1 for the younger wave half (wr==1)
# speedup vs baseline: 1.0026x; 1.0026x over previous
.LBB0_335:
	s_ashr_i32 s0, s6, 3
	s_add_u32 s30, s56, 0x1c000000
	s_addc_u32 s31, s57, 0
	s_add_i32 s0, s7, s0
	s_ashr_i32 s6, s0, 31
	s_lshr_b32 s6, s6, 22
	s_add_i32 s6, s0, s6
	s_ashr_i32 s7, s6, 10
	s_and_b32 s6, s6, 0xfffffc00
	s_sub_i32 s6, s0, s6
	s_sext_i32_i16 s0, s6
	s_bfe_u32 s0, s0, 0x3001c
	s_add_i32 s9, s6, s0
	s_sext_i32_i16 s0, s9
	s_and_b32 s9, s9, 0xfff8
	s_sub_i32 s6, s6, s9
	s_lshl_b32 s7, s7, 3
	s_sext_i32_i16 s6, s6
	s_lshr_b32 s1, s3, 8
	s_lshr_b32 s0, s0, 3
	s_add_i32 s42, s7, s6
	s_lshr_b32 s8, s3, 6
	s_ashr_i32 s43, s42, 31
	s_bfe_i64 s[10:11], s[0:1], 0x100000
	s_lshl_b32 s33, s8, 10
	s_lshl_b64 s[6:7], s[42:43], 20
	s_lshl_b64 s[10:11], s[10:11], 20
	s_add_u32 s46, s56, s10
	s_addc_u32 s47, s57, s11
	s_add_i32 s34, s33, 0
	s_add_i32 m0, s34, 0x10000
	v_mov_b32_e32 v133, 0
	global_load_lds_dwordx4 v132, s[46:47]
	s_add_i32 m0, s34, 0x12000
	s_add_u32 s44, s30, s6
	global_load_lds_dwordx4 v136, s[46:47]
	s_addc_u32 s45, s31, s7
	s_mov_b32 m0, s34
	s_add_i32 s35, s34, 0x2000
	global_load_lds_dwordx4 v130, s[44:45]
	s_mov_b32 m0, s35
	s_add_u32 s6, s46, 0x80000
	global_load_lds_dwordx4 v134, s[44:45]
	s_addc_u32 s7, s47, 0
	s_add_i32 m0, s34, 0x14000
	v_mov_b32_e32 v137, v133
	global_load_lds_dwordx4 v132, s[6:7]
	s_add_i32 m0, s34, 0x16000
	v_mov_b32_e32 v131, v133
	global_load_lds_dwordx4 v136, s[6:7]
	s_add_u32 s6, s44, 0x80000
	s_addc_u32 s7, s45, 0
	s_add_i32 s43, s34, 0x4000
	s_mov_b32 m0, s43
	s_add_i32 s60, s34, 0x6000
	global_load_lds_dwordx4 v130, s[6:7]
	s_mov_b32 m0, s60
	v_mov_b32_e32 v135, v133
	global_load_lds_dwordx4 v134, s[6:7]
	s_mov_b32 s61, 0
	v_lshl_add_u64 v[8:9], s[46:47], 0, v[132:133]
	v_lshl_add_u64 v[6:7], s[46:47], 0, v[136:137]
	v_lshl_add_u64 v[4:5], s[44:45], 0, v[130:131]
	s_cmp_lg_u32 s1, 1
	v_lshl_add_u64 v[2:3], s[44:45], 0, v[134:135]
	s_cbranch_scc1 .LBB0_337
	s_setprio 1
	s_barrier

.LBB0_344:
	s_ashr_i32 s37, s36, 31
	v_cmp_lt_i64_e32 vcc, s[38:39], v[142:143]
	s_lshl_b64 s[38:39], s[36:37], 20
	s_add_u32 s38, s30, s38
	s_addc_u32 s39, s31, s39
	s_and_b64 s[40:41], vcc, exec
	s_cselect_b32 s37, s39, s45
	s_cselect_b32 s72, s38, s44
	s_ashr_i32 s27, s26, 31
	s_lshl_b64 s[40:41], s[26:27], 20
	s_add_u32 s40, s56, s40
	s_addc_u32 s41, s57, s41
	s_and_b64 s[50:51], vcc, exec
	s_cselect_b32 s27, s41, s47
	s_cselect_b32 s73, s40, s46
	s_add_u32 s44, s44, 0x80080
	s_addc_u32 s45, s45, 0
	s_add_u32 s74, s46, 0x100
	v_mov_b32_e32 v2, 0
	s_addc_u32 s75, s47, 0
	s_mov_b32 s76, -2
	v_mov_b32_e32 v3, v2
	v_mov_b32_e32 v4, v2
	v_mov_b32_e32 v5, v2
	v_mov_b32_e32 v6, v2
	v_mov_b32_e32 v7, v2
	v_mov_b32_e32 v8, v2
	v_mov_b32_e32 v9, v2
	v_mov_b32_e32 v10, v2
	v_mov_b32_e32 v11, v2
	v_mov_b32_e32 v12, v2
	v_mov_b32_e32 v13, v2
	v_mov_b32_e32 v18, v2
	v_mov_b32_e32 v19, v2
	v_mov_b32_e32 v20, v2
	v_mov_b32_e32 v21, v2
	v_mov_b32_e32 v26, v2
	v_mov_b32_e32 v27, v2
	v_mov_b32_e32 v28, v2
	v_mov_b32_e32 v29, v2
	v_mov_b32_e32 v34, v2
	v_mov_b32_e32 v35, v2
	v_mov_b32_e32 v36, v2
	v_mov_b32_e32 v37, v2
	v_mov_b32_e32 v42, v2
	v_mov_b32_e32 v43, v2
	v_mov_b32_e32 v44, v2
	v_mov_b32_e32 v45, v2
	v_mov_b32_e32 v50, v2
	v_mov_b32_e32 v51, v2
	v_mov_b32_e32 v52, v2
	v_mov_b32_e32 v53, v2
	v_mov_b32_e32 v14, v2
	v_mov_b32_e32 v15, v2
	v_mov_b32_e32 v16, v2
	v_mov_b32_e32 v17, v2
	v_mov_b32_e32 v22, v2
	v_mov_b32_e32 v23, v2
	v_mov_b32_e32 v24, v2
	v_mov_b32_e32 v25, v2
	v_mov_b32_e32 v30, v2
	v_mov_b32_e32 v31, v2
	v_mov_b32_e32 v32, v2
	v_mov_b32_e32 v33, v2
	v_mov_b32_e32 v38, v2
	v_mov_b32_e32 v39, v2
	v_mov_b32_e32 v40, v2
	v_mov_b32_e32 v41, v2
	v_mov_b32_e32 v46, v2
	v_mov_b32_e32 v47, v2
	v_mov_b32_e32 v48, v2
	v_mov_b32_e32 v49, v2
	v_mov_b32_e32 v54, v2
	v_mov_b32_e32 v55, v2
	v_mov_b32_e32 v56, v2
	v_mov_b32_e32 v57, v2
	v_mov_b32_e32 v58, v2
	v_mov_b32_e32 v59, v2
	v_mov_b32_e32 v60, v2
	v_mov_b32_e32 v61, v2
	v_mov_b32_e32 v62, v2
	v_mov_b32_e32 v63, v2
	v_mov_b32_e32 v64, v2
	v_mov_b32_e32 v65, v2
	v_mov_b32_e32 v66, v2
	v_mov_b32_e32 v67, v2
	v_mov_b32_e32 v68, v2
	v_mov_b32_e32 v69, v2
	v_mov_b32_e32 v70, v2
	v_mov_b32_e32 v71, v2
	v_mov_b32_e32 v72, v2
	v_mov_b32_e32 v73, v2
	v_mov_b32_e32 v78, v2
	v_mov_b32_e32 v79, v2
	v_mov_b32_e32 v80, v2
	v_mov_b32_e32 v81, v2
	v_mov_b32_e32 v86, v2
	v_mov_b32_e32 v87, v2
	v_mov_b32_e32 v88, v2
	v_mov_b32_e32 v89, v2
	v_mov_b32_e32 v94, v2
	v_mov_b32_e32 v95, v2
	v_mov_b32_e32 v96, v2
	v_mov_b32_e32 v97, v2
	v_mov_b32_e32 v102, v2
	v_mov_b32_e32 v103, v2
	v_mov_b32_e32 v104, v2
	v_mov_b32_e32 v105, v2
	v_mov_b32_e32 v110, v2
	v_mov_b32_e32 v111, v2
	v_mov_b32_e32 v112, v2
	v_mov_b32_e32 v113, v2
	v_mov_b32_e32 v118, v2
	v_mov_b32_e32 v119, v2
	v_mov_b32_e32 v120, v2
	v_mov_b32_e32 v121, v2
	v_mov_b32_e32 v74, v2
	v_mov_b32_e32 v75, v2
	v_mov_b32_e32 v76, v2
	v_mov_b32_e32 v77, v2
	v_mov_b32_e32 v82, v2
	v_mov_b32_e32 v83, v2
	v_mov_b32_e32 v84, v2
	v_mov_b32_e32 v85, v2
	v_mov_b32_e32 v90, v2
	v_mov_b32_e32 v91, v2
	v_mov_b32_e32 v92, v2
	v_mov_b32_e32 v93, v2
	v_mov_b32_e32 v98, v2
	v_mov_b32_e32 v99, v2
	v_mov_b32_e32 v100, v2
	v_mov_b32_e32 v101, v2
	v_mov_b32_e32 v106, v2
	v_mov_b32_e32 v107, v2
	v_mov_b32_e32 v108, v2
	v_mov_b32_e32 v109, v2
	v_mov_b32_e32 v114, v2
	v_mov_b32_e32 v115, v2
	v_mov_b32_e32 v116, v2
	v_mov_b32_e32 v117, v2
	v_mov_b32_e32 v122, v2
	v_mov_b32_e32 v123, v2
	v_mov_b32_e32 v124, v2
	v_mov_b32_e32 v125, v2
	v_mov_b32_e32 v126, v2
	v_mov_b32_e32 v127, v2
	v_mov_b32_e32 v128, v2
	v_mov_b32_e32 v129, v2
	s_cmp_eq_u32 s99, 0
	s_cbranch_scc1 .LBB0_345
	ds_read_b128 v[164:167], v160
	ds_read_b128 v[168:171], v160 offset:1024
	ds_read_b128 v[172:175], v160 offset:2048
	ds_read_b128 v[176:179], v160 offset:3072
	s_add_u32 s46, s44, 0xfff80080
	s_addc_u32 s47, s45, -1
	s_cmp_eq_u32 s76, 28
	s_cselect_b32 s51, s37, s47
	s_cselect_b32 s50, s72, s46
	s_cselect_b32 s47, s27, s75
	s_cselect_b32 s46, s73, s74
	v_lshl_add_u64 v[148:149], s[44:45], 0, v[138:139]
	s_add_i32 m0, s34, 0xc000
	ds_read_b128 v[180:183], v161
	ds_read_b128 v[184:187], v161 offset:1024
	ds_read_b128 v[188:191], v161 offset:2048
	ds_read_b128 v[192:195], v161 offset:3072
	ds_read_b128 v[196:199], v161 offset:4096
	ds_read_b128 v[204:207], v161 offset:5120
	ds_read_b128 v[208:211], v161 offset:6144
	ds_read_b128 v[212:215], v161 offset:7168
	v_lshl_add_u64 v[148:149], s[44:45], 0, v[140:141]
	s_add_i32 m0, s34, 0xe000
	s_nop 0
	s_waitcnt lgkmcnt(8)
	s_barrier
	s_waitcnt lgkmcnt(0)
	s_waitcnt lgkmcnt(0)
	v_mfma_f32_16x16x32_bf16 v[126:129], v[164:167], v[180:183], v[126:129]
	v_mfma_f32_16x16x32_bf16 v[122:125], v[172:175], v[180:183], v[122:125]
	v_mfma_f32_16x16x32_bf16 v[114:117], v[164:167], v[188:191], v[114:117]
	v_mfma_f32_16x16x32_bf16 v[106:109], v[172:175], v[188:191], v[106:109]
	v_mfma_f32_16x16x32_bf16 v[98:101], v[164:167], v[196:199], v[98:101]
	v_mfma_f32_16x16x32_bf16 v[90:93], v[172:175], v[196:199], v[90:93]
	v_mfma_f32_16x16x32_bf16 v[82:85], v[164:167], v[208:211], v[82:85]
	v_mfma_f32_16x16x32_bf16 v[74:77], v[172:175], v[208:211], v[74:77]
	v_mfma_f32_16x16x32_bf16 v[126:129], v[168:171], v[184:187], v[126:129]
	v_mfma_f32_16x16x32_bf16 v[122:125], v[176:179], v[184:187], v[122:125]
	v_mfma_f32_16x16x32_bf16 v[114:117], v[168:171], v[192:195], v[114:117]
	v_mfma_f32_16x16x32_bf16 v[106:109], v[176:179], v[192:195], v[106:109]
	v_mfma_f32_16x16x32_bf16 v[98:101], v[168:171], v[204:207], v[98:101]
	v_mfma_f32_16x16x32_bf16 v[90:93], v[176:179], v[204:207], v[90:93]
	v_mfma_f32_16x16x32_bf16 v[82:85], v[168:171], v[212:215], v[82:85]
	v_mfma_f32_16x16x32_bf16 v[74:77], v[176:179], v[212:215], v[74:77]
	s_barrier
	s_add_i32 s77, s65, s33
	v_lshl_add_u64 v[148:149], s[46:47], 0, v[132:133]
	s_mov_b32 m0, s77
	ds_read_b128 v[216:219], v162
	ds_read_b128 v[220:223], v162 offset:1024
	ds_read_b128 v[224:227], v162 offset:2048
	ds_read_b128 v[228:231], v162 offset:3072
	global_load_lds_dwordx4 v[148:149], off
	v_lshl_add_u64 v[232:233], s[46:47], 0, v[136:137]
	s_add_i32 m0, s77, 0x2000
	s_nop 0
	global_load_lds_dwordx4 v[232:233], off
	s_barrier
	s_waitcnt lgkmcnt(0)
	s_waitcnt lgkmcnt(0)
	v_mfma_f32_16x16x32_bf16 v[118:121], v[216:219], v[180:183], v[118:121]
	v_mfma_f32_16x16x32_bf16 v[110:113], v[224:227], v[180:183], v[110:113]
	v_mfma_f32_16x16x32_bf16 v[102:105], v[216:219], v[188:191], v[102:105]
	v_mfma_f32_16x16x32_bf16 v[94:97], v[224:227], v[188:191], v[94:97]
	v_mfma_f32_16x16x32_bf16 v[86:89], v[216:219], v[196:199], v[86:89]
	v_mfma_f32_16x16x32_bf16 v[78:81], v[224:227], v[196:199], v[78:81]
	v_mfma_f32_16x16x32_bf16 v[70:73], v[216:219], v[208:211], v[70:73]
	v_mfma_f32_16x16x32_bf16 v[66:69], v[224:227], v[208:211], v[66:69]
	v_mfma_f32_16x16x32_bf16 v[118:121], v[220:223], v[184:187], v[118:121]
	v_mfma_f32_16x16x32_bf16 v[110:113], v[228:231], v[184:187], v[110:113]
	v_mfma_f32_16x16x32_bf16 v[102:105], v[220:223], v[192:195], v[102:105]
	v_mfma_f32_16x16x32_bf16 v[94:97], v[228:231], v[192:195], v[94:97]
	v_mfma_f32_16x16x32_bf16 v[86:89], v[220:223], v[204:207], v[86:89]
	v_mfma_f32_16x16x32_bf16 v[78:81], v[228:231], v[204:207], v[78:81]
	v_mfma_f32_16x16x32_bf16 v[70:73], v[220:223], v[212:215], v[70:73]
	v_mfma_f32_16x16x32_bf16 v[66:69], v[228:231], v[212:215], v[66:69]
	s_mov_b32 m0, s34
	v_lshl_add_u64 v[234:235], s[50:51], 0, v[130:131]
	s_barrier
	ds_read_b128 v[180:183], v161 offset:16384
	ds_read_b128 v[184:187], v161 offset:17408
	ds_read_b128 v[188:191], v161 offset:18432
	ds_read_b128 v[192:195], v161 offset:19456
	ds_read_b128 v[196:199], v161 offset:20480
	ds_read_b128 v[204:207], v161 offset:21504
	ds_read_b128 v[208:211], v161 offset:22528
	ds_read_b128 v[212:215], v161 offset:23552
	global_load_lds_dwordx4 v[234:235], off
	v_lshl_add_u64 v[236:237], s[50:51], 0, v[134:135]
	s_mov_b32 m0, s35
	s_nop 0
	global_load_lds_dwordx4 v[236:237], off
	s_barrier
	s_waitcnt lgkmcnt(0)
	s_waitcnt lgkmcnt(0)
	v_mfma_f32_16x16x32_bf16 v[62:65], v[164:167], v[180:183], v[62:65]
	v_mfma_f32_16x16x32_bf16 v[58:61], v[172:175], v[180:183], v[58:61]
	v_mfma_f32_16x16x32_bf16 v[54:57], v[164:167], v[188:191], v[54:57]
	v_mfma_f32_16x16x32_bf16 v[46:49], v[172:175], v[188:191], v[46:49]
	v_mfma_f32_16x16x32_bf16 v[38:41], v[164:167], v[196:199], v[38:41]
	v_mfma_f32_16x16x32_bf16 v[30:33], v[172:175], v[196:199], v[30:33]
	v_mfma_f32_16x16x32_bf16 v[22:25], v[164:167], v[208:211], v[22:25]
	v_mfma_f32_16x16x32_bf16 v[14:17], v[172:175], v[208:211], v[14:17]
	v_mfma_f32_16x16x32_bf16 v[62:65], v[168:171], v[184:187], v[62:65]
	v_mfma_f32_16x16x32_bf16 v[58:61], v[176:179], v[184:187], v[58:61]
	v_mfma_f32_16x16x32_bf16 v[54:57], v[168:171], v[192:195], v[54:57]
	v_mfma_f32_16x16x32_bf16 v[46:49], v[176:179], v[192:195], v[46:49]
	v_mfma_f32_16x16x32_bf16 v[38:41], v[168:171], v[204:207], v[38:41]
	v_mfma_f32_16x16x32_bf16 v[30:33], v[176:179], v[204:207], v[30:33]
	v_mfma_f32_16x16x32_bf16 v[22:25], v[168:171], v[212:215], v[22:25]
	v_mfma_f32_16x16x32_bf16 v[14:17], v[176:179], v[212:215], v[14:17]
	s_barrier
	s_add_u32 s78, s46, 0x80000
	s_addc_u32 s79, s47, 0
	s_add_i32 s77, s66, s33
	v_lshl_add_u64 v[164:165], s[78:79], 0, v[132:133]
	s_mov_b32 m0, s77
	s_nop 0
	global_load_lds_dwordx4 v[164:165], off
	v_lshl_add_u64 v[164:165], s[78:79], 0, v[136:137]
	s_add_i32 m0, s77, 0x2000
	s_nop 0
	global_load_lds_dwordx4 v[164:165], off
	s_waitcnt vmcnt(22)
	s_barrier
	v_mfma_f32_16x16x32_bf16 v[50:53], v[216:219], v[180:183], v[50:53]
	v_mfma_f32_16x16x32_bf16 v[42:45], v[224:227], v[180:183], v[42:45]
	v_mfma_f32_16x16x32_bf16 v[34:37], v[216:219], v[188:191], v[34:37]
	v_mfma_f32_16x16x32_bf16 v[26:29], v[224:227], v[188:191], v[26:29]
	v_mfma_f32_16x16x32_bf16 v[18:21], v[216:219], v[196:199], v[18:21]
	v_mfma_f32_16x16x32_bf16 v[10:13], v[224:227], v[196:199], v[10:13]
	v_mfma_f32_16x16x32_bf16 v[6:9], v[216:219], v[208:211], v[6:9]
	v_mfma_f32_16x16x32_bf16 v[2:5], v[224:227], v[208:211], v[2:5]
	v_mfma_f32_16x16x32_bf16 v[50:53], v[220:223], v[184:187], v[50:53]
	v_mfma_f32_16x16x32_bf16 v[42:45], v[228:231], v[184:187], v[42:45]
	v_mfma_f32_16x16x32_bf16 v[34:37], v[220:223], v[192:195], v[34:37]
	v_mfma_f32_16x16x32_bf16 v[26:29], v[228:231], v[192:195], v[26:29]
	v_mfma_f32_16x16x32_bf16 v[18:21], v[220:223], v[204:207], v[18:21]
	v_mfma_f32_16x16x32_bf16 v[10:13], v[228:231], v[204:207], v[10:13]
	v_mfma_f32_16x16x32_bf16 v[6:9], v[220:223], v[212:215], v[6:9]
	v_mfma_f32_16x16x32_bf16 v[2:5], v[228:231], v[212:215], v[2:5]
	s_add_i32 s77, 0, 0x18000
	v_add_u32_e32 v163, s77, v158
	s_barrier
	s_branch .Ltb_mid_g1
.LBB0_345:
	ds_read_b128 v[164:167], v160
	ds_read_b128 v[168:171], v160 offset:1024
	ds_read_b128 v[172:175], v160 offset:2048
	ds_read_b128 v[176:179], v160 offset:3072
	s_add_u32 s46, s44, 0xfff80080
	s_addc_u32 s47, s45, -1
	s_cmp_eq_u32 s76, 28
	s_cselect_b32 s51, s37, s47
	s_cselect_b32 s50, s72, s46
	s_cselect_b32 s47, s27, s75
	s_cselect_b32 s46, s73, s74
	v_lshl_add_u64 v[148:149], s[44:45], 0, v[138:139]
	s_add_i32 m0, s34, 0xc000
	ds_read_b128 v[180:183], v161
	ds_read_b128 v[184:187], v161 offset:1024
	ds_read_b128 v[188:191], v161 offset:2048
	ds_read_b128 v[192:195], v161 offset:3072
	ds_read_b128 v[196:199], v161 offset:4096
	ds_read_b128 v[204:207], v161 offset:5120
	ds_read_b128 v[208:211], v161 offset:6144
	ds_read_b128 v[212:215], v161 offset:7168
	global_load_lds_dwordx4 v[148:149], off
	v_lshl_add_u64 v[148:149], s[44:45], 0, v[140:141]
	s_add_i32 m0, s34, 0xe000
	s_nop 0
	global_load_lds_dwordx4 v[148:149], off
	s_waitcnt lgkmcnt(8)
	s_barrier
	s_waitcnt lgkmcnt(0)
	s_waitcnt lgkmcnt(0)
	v_mfma_f32_16x16x32_bf16 v[126:129], v[164:167], v[180:183], v[126:129]
	v_mfma_f32_16x16x32_bf16 v[122:125], v[172:175], v[180:183], v[122:125]
	v_mfma_f32_16x16x32_bf16 v[114:117], v[164:167], v[188:191], v[114:117]
	v_mfma_f32_16x16x32_bf16 v[106:109], v[172:175], v[188:191], v[106:109]
	v_mfma_f32_16x16x32_bf16 v[98:101], v[164:167], v[196:199], v[98:101]
	v_mfma_f32_16x16x32_bf16 v[90:93], v[172:175], v[196:199], v[90:93]
	v_mfma_f32_16x16x32_bf16 v[82:85], v[164:167], v[208:211], v[82:85]
	v_mfma_f32_16x16x32_bf16 v[74:77], v[172:175], v[208:211], v[74:77]
	v_mfma_f32_16x16x32_bf16 v[126:129], v[168:171], v[184:187], v[126:129]
	v_mfma_f32_16x16x32_bf16 v[122:125], v[176:179], v[184:187], v[122:125]
	v_mfma_f32_16x16x32_bf16 v[114:117], v[168:171], v[192:195], v[114:117]
	v_mfma_f32_16x16x32_bf16 v[106:109], v[176:179], v[192:195], v[106:109]
	v_mfma_f32_16x16x32_bf16 v[98:101], v[168:171], v[204:207], v[98:101]
	v_mfma_f32_16x16x32_bf16 v[90:93], v[176:179], v[204:207], v[90:93]
	v_mfma_f32_16x16x32_bf16 v[82:85], v[168:171], v[212:215], v[82:85]
	v_mfma_f32_16x16x32_bf16 v[74:77], v[176:179], v[212:215], v[74:77]
	s_barrier
	s_add_i32 s77, s65, s33
	v_lshl_add_u64 v[148:149], s[46:47], 0, v[132:133]
	s_mov_b32 m0, s77
	ds_read_b128 v[216:219], v162
	ds_read_b128 v[220:223], v162 offset:1024
	ds_read_b128 v[224:227], v162 offset:2048
	ds_read_b128 v[228:231], v162 offset:3072
	global_load_lds_dwordx4 v[148:149], off
	v_lshl_add_u64 v[232:233], s[46:47], 0, v[136:137]
	s_add_i32 m0, s77, 0x2000
	s_nop 0
	global_load_lds_dwordx4 v[232:233], off
	s_barrier
	s_waitcnt lgkmcnt(0)
	s_waitcnt lgkmcnt(0)
	v_mfma_f32_16x16x32_bf16 v[118:121], v[216:219], v[180:183], v[118:121]
	v_mfma_f32_16x16x32_bf16 v[110:113], v[224:227], v[180:183], v[110:113]
	v_mfma_f32_16x16x32_bf16 v[102:105], v[216:219], v[188:191], v[102:105]
	v_mfma_f32_16x16x32_bf16 v[94:97], v[224:227], v[188:191], v[94:97]
	v_mfma_f32_16x16x32_bf16 v[86:89], v[216:219], v[196:199], v[86:89]
	v_mfma_f32_16x16x32_bf16 v[78:81], v[224:227], v[196:199], v[78:81]
	v_mfma_f32_16x16x32_bf16 v[70:73], v[216:219], v[208:211], v[70:73]
	v_mfma_f32_16x16x32_bf16 v[66:69], v[224:227], v[208:211], v[66:69]
	v_mfma_f32_16x16x32_bf16 v[118:121], v[220:223], v[184:187], v[118:121]
	v_mfma_f32_16x16x32_bf16 v[110:113], v[228:231], v[184:187], v[110:113]
	v_mfma_f32_16x16x32_bf16 v[102:105], v[220:223], v[192:195], v[102:105]
	v_mfma_f32_16x16x32_bf16 v[94:97], v[228:231], v[192:195], v[94:97]
	v_mfma_f32_16x16x32_bf16 v[86:89], v[220:223], v[204:207], v[86:89]
	v_mfma_f32_16x16x32_bf16 v[78:81], v[228:231], v[204:207], v[78:81]
	v_mfma_f32_16x16x32_bf16 v[70:73], v[220:223], v[212:215], v[70:73]
	v_mfma_f32_16x16x32_bf16 v[66:69], v[228:231], v[212:215], v[66:69]
	s_mov_b32 m0, s34
	v_lshl_add_u64 v[234:235], s[50:51], 0, v[130:131]
	s_barrier
	ds_read_b128 v[180:183], v161 offset:16384
	ds_read_b128 v[184:187], v161 offset:17408
	ds_read_b128 v[188:191], v161 offset:18432
	ds_read_b128 v[192:195], v161 offset:19456
	ds_read_b128 v[196:199], v161 offset:20480
	ds_read_b128 v[204:207], v161 offset:21504
	ds_read_b128 v[208:211], v161 offset:22528
	ds_read_b128 v[212:215], v161 offset:23552
	global_load_lds_dwordx4 v[234:235], off
	v_lshl_add_u64 v[236:237], s[50:51], 0, v[134:135]
	s_mov_b32 m0, s35
	s_nop 0
	global_load_lds_dwordx4 v[236:237], off
	s_barrier
	s_waitcnt lgkmcnt(0)
	s_waitcnt lgkmcnt(0)
	v_mfma_f32_16x16x32_bf16 v[62:65], v[164:167], v[180:183], v[62:65]
	v_mfma_f32_16x16x32_bf16 v[58:61], v[172:175], v[180:183], v[58:61]
	v_mfma_f32_16x16x32_bf16 v[54:57], v[164:167], v[188:191], v[54:57]
	v_mfma_f32_16x16x32_bf16 v[46:49], v[172:175], v[188:191], v[46:49]
	v_mfma_f32_16x16x32_bf16 v[38:41], v[164:167], v[196:199], v[38:41]
	v_mfma_f32_16x16x32_bf16 v[30:33], v[172:175], v[196:199], v[30:33]
	v_mfma_f32_16x16x32_bf16 v[22:25], v[164:167], v[208:211], v[22:25]
	v_mfma_f32_16x16x32_bf16 v[14:17], v[172:175], v[208:211], v[14:17]
	v_mfma_f32_16x16x32_bf16 v[62:65], v[168:171], v[184:187], v[62:65]
	v_mfma_f32_16x16x32_bf16 v[58:61], v[176:179], v[184:187], v[58:61]
	v_mfma_f32_16x16x32_bf16 v[54:57], v[168:171], v[192:195], v[54:57]
	v_mfma_f32_16x16x32_bf16 v[46:49], v[176:179], v[192:195], v[46:49]
	v_mfma_f32_16x16x32_bf16 v[38:41], v[168:171], v[204:207], v[38:41]
	v_mfma_f32_16x16x32_bf16 v[30:33], v[176:179], v[204:207], v[30:33]
	v_mfma_f32_16x16x32_bf16 v[22:25], v[168:171], v[212:215], v[22:25]
	v_mfma_f32_16x16x32_bf16 v[14:17], v[176:179], v[212:215], v[14:17]
	s_barrier
	s_add_u32 s78, s46, 0x80000
	s_addc_u32 s79, s47, 0
	s_add_i32 s77, s66, s33
	v_lshl_add_u64 v[164:165], s[78:79], 0, v[132:133]
	s_mov_b32 m0, s77
	s_nop 0
	global_load_lds_dwordx4 v[164:165], off
	v_lshl_add_u64 v[164:165], s[78:79], 0, v[136:137]
	s_add_i32 m0, s77, 0x2000
	s_nop 0
	global_load_lds_dwordx4 v[164:165], off
	s_waitcnt vmcnt(6)
	s_barrier
	v_mfma_f32_16x16x32_bf16 v[50:53], v[216:219], v[180:183], v[50:53]
	v_mfma_f32_16x16x32_bf16 v[42:45], v[224:227], v[180:183], v[42:45]
	v_mfma_f32_16x16x32_bf16 v[34:37], v[216:219], v[188:191], v[34:37]
	v_mfma_f32_16x16x32_bf16 v[26:29], v[224:227], v[188:191], v[26:29]
	v_mfma_f32_16x16x32_bf16 v[18:21], v[216:219], v[196:199], v[18:21]
	v_mfma_f32_16x16x32_bf16 v[10:13], v[224:227], v[196:199], v[10:13]
	v_mfma_f32_16x16x32_bf16 v[6:9], v[216:219], v[208:211], v[6:9]
	v_mfma_f32_16x16x32_bf16 v[2:5], v[224:227], v[208:211], v[2:5]
	v_mfma_f32_16x16x32_bf16 v[50:53], v[220:223], v[184:187], v[50:53]
	v_mfma_f32_16x16x32_bf16 v[42:45], v[228:231], v[184:187], v[42:45]
	v_mfma_f32_16x16x32_bf16 v[34:37], v[220:223], v[192:195], v[34:37]
	v_mfma_f32_16x16x32_bf16 v[26:29], v[228:231], v[192:195], v[26:29]
	v_mfma_f32_16x16x32_bf16 v[18:21], v[220:223], v[204:207], v[18:21]
	v_mfma_f32_16x16x32_bf16 v[10:13], v[228:231], v[204:207], v[10:13]
	v_mfma_f32_16x16x32_bf16 v[6:9], v[220:223], v[212:215], v[6:9]
	v_mfma_f32_16x16x32_bf16 v[2:5], v[228:231], v[212:215], v[2:5]
	s_add_i32 s77, 0, 0x18000
	v_add_u32_e32 v163, s77, v158
	s_barrier
.Ltb_mid_g1:
	ds_read_b128 v[164:167], v163
	ds_read_b128 v[168:171], v163 offset:1024
	ds_read_b128 v[172:175], v163 offset:2048
	ds_read_b128 v[176:179], v163 offset:3072
	s_add_u32 s50, s50, 0x80000
	s_addc_u32 s51, s51, 0
	s_mov_b32 m0, s43
	v_lshl_add_u64 v[216:217], s[50:51], 0, v[130:131]
	ds_read_b128 v[180:183], v161 offset:32768
	ds_read_b128 v[184:187], v161 offset:33792
	ds_read_b128 v[188:191], v161 offset:34816
	ds_read_b128 v[192:195], v161 offset:35840
	ds_read_b128 v[196:199], v161 offset:36864
	ds_read_b128 v[204:207], v161 offset:37888
	ds_read_b128 v[208:211], v161 offset:38912
	ds_read_b128 v[212:215], v161 offset:39936
	global_load_lds_dwordx4 v[216:217], off
	v_lshl_add_u64 v[216:217], s[50:51], 0, v[134:135]
	s_mov_b32 m0, s60
	s_nop 0
	global_load_lds_dwordx4 v[216:217], off
	s_waitcnt lgkmcnt(8)
	s_barrier
	s_waitcnt lgkmcnt(0)
	s_waitcnt lgkmcnt(0)
	v_mfma_f32_16x16x32_bf16 v[126:129], v[164:167], v[180:183], v[126:129]
	v_mfma_f32_16x16x32_bf16 v[122:125], v[172:175], v[180:183], v[122:125]
	v_mfma_f32_16x16x32_bf16 v[114:117], v[164:167], v[188:191], v[114:117]
	v_mfma_f32_16x16x32_bf16 v[106:109], v[172:175], v[188:191], v[106:109]
	v_mfma_f32_16x16x32_bf16 v[98:101], v[164:167], v[196:199], v[98:101]
	v_mfma_f32_16x16x32_bf16 v[90:93], v[172:175], v[196:199], v[90:93]
	v_mfma_f32_16x16x32_bf16 v[82:85], v[164:167], v[208:211], v[82:85]
	v_mfma_f32_16x16x32_bf16 v[74:77], v[172:175], v[208:211], v[74:77]
	v_mfma_f32_16x16x32_bf16 v[126:129], v[168:171], v[184:187], v[126:129]
	v_mfma_f32_16x16x32_bf16 v[122:125], v[176:179], v[184:187], v[122:125]
	v_mfma_f32_16x16x32_bf16 v[114:117], v[168:171], v[192:195], v[114:117]
	v_mfma_f32_16x16x32_bf16 v[106:109], v[176:179], v[192:195], v[106:109]
	v_mfma_f32_16x16x32_bf16 v[98:101], v[168:171], v[204:207], v[98:101]
	v_mfma_f32_16x16x32_bf16 v[90:93], v[176:179], v[204:207], v[90:93]
	v_mfma_f32_16x16x32_bf16 v[82:85], v[168:171], v[212:215], v[82:85]
	v_mfma_f32_16x16x32_bf16 v[74:77], v[176:179], v[212:215], v[74:77]
	s_barrier
	s_add_i32 s50, 0, 0x1c000
	s_add_i32 s51, s77, s33
	v_add_u32_e32 v163, s50, v158
	v_lshl_add_u64 v[148:149], v[148:149], 0, s[8:9]
	s_mov_b32 m0, s51
	ds_read_b128 v[216:219], v163
	ds_read_b128 v[220:223], v163 offset:1024
	ds_read_b128 v[224:227], v163 offset:2048
	ds_read_b128 v[228:231], v163 offset:3072
	global_load_lds_dwordx4 v[148:149], off
	v_lshl_add_u64 v[148:149], v[232:233], 0, s[8:9]
	s_add_i32 m0, s51, 0x2000
	s_nop 0
	global_load_lds_dwordx4 v[148:149], off
	s_barrier
	s_waitcnt lgkmcnt(0)
	s_waitcnt lgkmcnt(0)
	v_mfma_f32_16x16x32_bf16 v[118:121], v[216:219], v[180:183], v[118:121]
	v_mfma_f32_16x16x32_bf16 v[110:113], v[224:227], v[180:183], v[110:113]
	v_mfma_f32_16x16x32_bf16 v[102:105], v[216:219], v[188:191], v[102:105]
	v_mfma_f32_16x16x32_bf16 v[94:97], v[224:227], v[188:191], v[94:97]
	v_mfma_f32_16x16x32_bf16 v[86:89], v[216:219], v[196:199], v[86:89]
	v_mfma_f32_16x16x32_bf16 v[78:81], v[224:227], v[196:199], v[78:81]
	v_mfma_f32_16x16x32_bf16 v[70:73], v[216:219], v[208:211], v[70:73]
	v_mfma_f32_16x16x32_bf16 v[66:69], v[224:227], v[208:211], v[66:69]
	v_mfma_f32_16x16x32_bf16 v[118:121], v[220:223], v[184:187], v[118:121]
	v_mfma_f32_16x16x32_bf16 v[110:113], v[228:231], v[184:187], v[110:113]
	v_mfma_f32_16x16x32_bf16 v[102:105], v[220:223], v[192:195], v[102:105]
	v_mfma_f32_16x16x32_bf16 v[94:97], v[228:231], v[192:195], v[94:97]
	v_mfma_f32_16x16x32_bf16 v[86:89], v[220:223], v[204:207], v[86:89]
	v_mfma_f32_16x16x32_bf16 v[78:81], v[228:231], v[204:207], v[78:81]
	v_mfma_f32_16x16x32_bf16 v[70:73], v[220:223], v[212:215], v[70:73]
	v_mfma_f32_16x16x32_bf16 v[66:69], v[228:231], v[212:215], v[66:69]
	s_mov_b32 m0, s62
	v_lshl_add_u64 v[148:149], v[234:235], 0, s[8:9]
	s_barrier
	ds_read_b128 v[180:183], v161 offset:49152
	ds_read_b128 v[184:187], v161 offset:50176
	ds_read_b128 v[188:191], v161 offset:51200
	ds_read_b128 v[192:195], v161 offset:52224
	ds_read_b128 v[196:199], v161 offset:53248
	ds_read_b128 v[204:207], v161 offset:54272
	ds_read_b128 v[208:211], v161 offset:55296
	ds_read_b128 v[212:215], v161 offset:56320
	global_load_lds_dwordx4 v[148:149], off
	v_lshl_add_u64 v[148:149], v[236:237], 0, s[8:9]
	s_mov_b32 m0, s63
	s_nop 0
	global_load_lds_dwordx4 v[148:149], off
	s_barrier
	s_waitcnt lgkmcnt(0)
	s_waitcnt lgkmcnt(0)
	v_mfma_f32_16x16x32_bf16 v[62:65], v[164:167], v[180:183], v[62:65]
	v_mfma_f32_16x16x32_bf16 v[58:61], v[172:175], v[180:183], v[58:61]
	v_mfma_f32_16x16x32_bf16 v[54:57], v[164:167], v[188:191], v[54:57]
	v_mfma_f32_16x16x32_bf16 v[46:49], v[172:175], v[188:191], v[46:49]
	v_mfma_f32_16x16x32_bf16 v[38:41], v[164:167], v[196:199], v[38:41]
	v_mfma_f32_16x16x32_bf16 v[30:33], v[172:175], v[196:199], v[30:33]
	v_mfma_f32_16x16x32_bf16 v[22:25], v[164:167], v[208:211], v[22:25]
	v_mfma_f32_16x16x32_bf16 v[14:17], v[172:175], v[208:211], v[14:17]
	v_mfma_f32_16x16x32_bf16 v[62:65], v[168:171], v[184:187], v[62:65]
	v_mfma_f32_16x16x32_bf16 v[58:61], v[176:179], v[184:187], v[58:61]
	v_mfma_f32_16x16x32_bf16 v[54:57], v[168:171], v[192:195], v[54:57]
	v_mfma_f32_16x16x32_bf16 v[46:49], v[176:179], v[192:195], v[46:49]
	v_mfma_f32_16x16x32_bf16 v[38:41], v[168:171], v[204:207], v[38:41]
	v_mfma_f32_16x16x32_bf16 v[30:33], v[176:179], v[204:207], v[30:33]
	v_mfma_f32_16x16x32_bf16 v[22:25], v[168:171], v[212:215], v[22:25]
	v_mfma_f32_16x16x32_bf16 v[14:17], v[176:179], v[212:215], v[14:17]
	s_barrier
	s_add_u32 s46, s46, 0x80080
	s_addc_u32 s47, s47, 0
	s_add_i32 s50, s50, s33
	v_lshl_add_u64 v[148:149], s[46:47], 0, v[132:133]
	s_mov_b32 m0, s50
	s_nop 0
	global_load_lds_dwordx4 v[148:149], off
	v_lshl_add_u64 v[148:149], s[46:47], 0, v[136:137]
	s_add_i32 m0, s50, 0x2000
	s_nop 0
	global_load_lds_dwordx4 v[148:149], off
	s_waitcnt vmcnt(6)
	s_barrier
	v_mfma_f32_16x16x32_bf16 v[50:53], v[216:219], v[180:183], v[50:53]
	v_mfma_f32_16x16x32_bf16 v[42:45], v[224:227], v[180:183], v[42:45]
	v_mfma_f32_16x16x32_bf16 v[34:37], v[216:219], v[188:191], v[34:37]
	v_mfma_f32_16x16x32_bf16 v[26:29], v[224:227], v[188:191], v[26:29]
	v_mfma_f32_16x16x32_bf16 v[18:21], v[216:219], v[196:199], v[18:21]
	v_mfma_f32_16x16x32_bf16 v[10:13], v[224:227], v[196:199], v[10:13]
	v_mfma_f32_16x16x32_bf16 v[6:9], v[216:219], v[208:211], v[6:9]
	v_mfma_f32_16x16x32_bf16 v[2:5], v[224:227], v[208:211], v[2:5]
	v_mfma_f32_16x16x32_bf16 v[50:53], v[220:223], v[184:187], v[50:53]
	v_mfma_f32_16x16x32_bf16 v[42:45], v[228:231], v[184:187], v[42:45]
	v_mfma_f32_16x16x32_bf16 v[34:37], v[220:223], v[192:195], v[34:37]
	v_mfma_f32_16x16x32_bf16 v[26:29], v[228:231], v[192:195], v[26:29]
	v_mfma_f32_16x16x32_bf16 v[18:21], v[220:223], v[204:207], v[18:21]
	v_mfma_f32_16x16x32_bf16 v[10:13], v[228:231], v[204:207], v[10:13]
	v_mfma_f32_16x16x32_bf16 v[6:9], v[220:223], v[212:215], v[6:9]
	v_mfma_f32_16x16x32_bf16 v[2:5], v[228:231], v[212:215], v[2:5]
	s_add_i32 s76, s76, 2
	s_add_u32 s44, s44, 0x100
	s_addc_u32 s45, s45, 0
	s_add_u32 s74, s74, 0x100
	s_addc_u32 s75, s75, 0
	s_cmp_gt_u32 s76, 29
	s_barrier
	s_cbranch_scc0 .LBB0_345
	s_add_u32 s100, s72, 0x80080
	s_addc_u32 s101, s37, 0
	v_lshl_add_u64 v[148:149], s[100:101], 0, v[138:139]
	s_add_i32 m0, s34, 0xc000
	s_nop 0
	global_load_lds_dwordx4 v[148:149], off
	v_lshl_add_u64 v[148:149], s[100:101], 0, v[140:141]
	s_add_i32 m0, s34, 0xe000
	s_nop 0
	global_load_lds_dwordx4 v[148:149], off
	s_mov_b32 s99, 1
	v_lshl_add_u32 v164, s42, 8, v157
	v_lshl_or_b32 v148, s71, 8, v159
	v_ashrrev_i32_e32 v165, 31, v164
	v_ashrrev_i32_e32 v149, 31, v148
	v_lshlrev_b64 v[166:167], 16, v[164:165]
	v_lshl_add_u64 v[166:167], s[6:7], 0, v[166:167]
	v_lshlrev_b64 v[168:169], 1, v[148:149]
	v_lshl_add_u64 v[148:149], v[166:167], 0, v[168:169]
	v_cvt_pk_bf16_f32 v126, v126, v127
	v_cvt_pk_bf16_f32 v127, v128, v129
	v_cvt_pk_bf16_f32 v128, v122, v123
	v_cvt_pk_bf16_f32 v129, v124, v125
	global_store_dwordx4 v[148:149], v[126:129], off
	v_cvt_pk_bf16_f32 v118, v118, v119
	v_cvt_pk_bf16_f32 v119, v120, v121
	v_cvt_pk_bf16_f32 v120, v110, v111
	v_or_b32_e32 v110, 16, v164
	v_ashrrev_i32_e32 v111, 31, v110
	v_lshlrev_b64 v[110:111], 16, v[110:111]
	v_lshl_add_u64 v[110:111], s[6:7], 0, v[110:111]
	v_cvt_pk_bf16_f32 v121, v112, v113
	global_store_dwordx4 v[148:149], v[118:121], off offset:256
	s_mov_b32 s71, s26
	s_mov_b32 s42, s36
	v_lshl_add_u64 v[118:119], v[110:111], 0, v[168:169]
	v_cvt_pk_bf16_f32 v110, v114, v115
	v_cvt_pk_bf16_f32 v111, v116, v117
	v_cvt_pk_bf16_f32 v112, v106, v107
	v_cvt_pk_bf16_f32 v113, v108, v109
	global_store_dwordx4 v[118:119], v[110:113], off
	v_cvt_pk_bf16_f32 v102, v102, v103
	v_cvt_pk_bf16_f32 v103, v104, v105
	v_cvt_pk_bf16_f32 v104, v94, v95
	v_or_b32_e32 v94, 32, v164
	v_ashrrev_i32_e32 v95, 31, v94
	v_lshlrev_b64 v[94:95], 16, v[94:95]
	v_lshl_add_u64 v[94:95], s[6:7], 0, v[94:95]
	v_cvt_pk_bf16_f32 v105, v96, v97
	global_store_dwordx4 v[118:119], v[102:105], off offset:256
	s_mov_b64 s[46:47], s[40:41]
	s_mov_b64 s[44:45], s[38:39]
	v_lshl_add_u64 v[102:103], v[94:95], 0, v[168:169]
	v_cvt_pk_bf16_f32 v94, v98, v99
	v_cvt_pk_bf16_f32 v95, v100, v101
	v_cvt_pk_bf16_f32 v96, v90, v91
	v_cvt_pk_bf16_f32 v97, v92, v93
	global_store_dwordx4 v[102:103], v[94:97], off
	v_cvt_pk_bf16_f32 v86, v86, v87
	v_cvt_pk_bf16_f32 v87, v88, v89
	v_cvt_pk_bf16_f32 v88, v78, v79
	v_or_b32_e32 v78, 48, v164
	v_ashrrev_i32_e32 v79, 31, v78
	v_lshlrev_b64 v[78:79], 16, v[78:79]
	v_lshl_add_u64 v[78:79], s[6:7], 0, v[78:79]
	v_cvt_pk_bf16_f32 v89, v80, v81
	global_store_dwordx4 v[102:103], v[86:89], off offset:256
	s_nop 1
	v_lshl_add_u64 v[86:87], v[78:79], 0, v[168:169]
	v_cvt_pk_bf16_f32 v78, v82, v83
	v_cvt_pk_bf16_f32 v79, v84, v85
	v_cvt_pk_bf16_f32 v80, v74, v75
	v_cvt_pk_bf16_f32 v81, v76, v77
	global_store_dwordx4 v[86:87], v[78:81], off
	v_cvt_pk_bf16_f32 v70, v70, v71
	v_cvt_pk_bf16_f32 v71, v72, v73
	v_cvt_pk_bf16_f32 v72, v66, v67
	v_cvt_pk_bf16_f32 v73, v68, v69
	global_store_dwordx4 v[86:87], v[70:73], off offset:256
	v_cvt_pk_bf16_f32 v62, v62, v63
	v_cvt_pk_bf16_f32 v63, v64, v65
	v_cvt_pk_bf16_f32 v64, v58, v59
	v_add_co_u32_e32 v58, vcc, s67, v148
	v_lshl_add_u64 v[66:67], v[148:149], 0, s[10:11]
	s_nop 0
	v_addc_co_u32_e32 v59, vcc, 0, v149, vcc
	v_cvt_pk_bf16_f32 v65, v60, v61
	global_store_dwordx4 v[58:59], v[62:65], off
	v_cvt_pk_bf16_f32 v50, v50, v51
	v_cvt_pk_bf16_f32 v51, v52, v53
	v_cvt_pk_bf16_f32 v52, v42, v43
	v_cvt_pk_bf16_f32 v53, v44, v45
	global_store_dwordx4 v[66:67], v[50:53], off offset:256
	v_cvt_pk_bf16_f32 v42, v54, v55
	v_cvt_pk_bf16_f32 v43, v56, v57
	v_cvt_pk_bf16_f32 v44, v46, v47
	v_add_co_u32_e32 v46, vcc, s68, v148
	s_nop 0
	v_lshl_add_u64 v[50:51], v[148:149], 0, s[16:17]
	v_addc_co_u32_e32 v47, vcc, 0, v149, vcc
	v_cvt_pk_bf16_f32 v45, v48, v49
	global_store_dwordx4 v[46:47], v[42:45], off
	v_cvt_pk_bf16_f32 v34, v34, v35
	v_cvt_pk_bf16_f32 v35, v36, v37
	v_cvt_pk_bf16_f32 v36, v26, v27
	v_cvt_pk_bf16_f32 v37, v28, v29
	global_store_dwordx4 v[50:51], v[34:37], off offset:256
	v_cvt_pk_bf16_f32 v26, v38, v39
	v_cvt_pk_bf16_f32 v27, v40, v41
	v_cvt_pk_bf16_f32 v28, v30, v31
	v_add_co_u32_e32 v30, vcc, s69, v148
	s_nop 0
	v_lshl_add_u64 v[34:35], v[148:149], 0, s[18:19]
	v_addc_co_u32_e32 v31, vcc, 0, v149, vcc
	v_cvt_pk_bf16_f32 v29, v32, v33
	global_store_dwordx4 v[30:31], v[26:29], off
	v_cvt_pk_bf16_f32 v18, v18, v19
	v_cvt_pk_bf16_f32 v19, v20, v21
	v_cvt_pk_bf16_f32 v20, v10, v11
	v_cvt_pk_bf16_f32 v21, v12, v13
	global_store_dwordx4 v[34:35], v[18:21], off offset:256
	v_cvt_pk_bf16_f32 v10, v22, v23
	v_cvt_pk_bf16_f32 v11, v24, v25
	v_cvt_pk_bf16_f32 v12, v14, v15
	v_add_co_u32_e32 v14, vcc, s70, v148
	s_nop 0
	v_lshl_add_u64 v[18:19], v[148:149], 0, s[24:25]
	v_addc_co_u32_e32 v15, vcc, 0, v149, vcc
	s_and_b64 vcc, exec, s[0:1]
	v_cvt_pk_bf16_f32 v13, v16, v17
	global_store_dwordx4 v[14:15], v[10:13], off
	v_cvt_pk_bf16_f32 v6, v6, v7
	v_cvt_pk_bf16_f32 v7, v8, v9
	v_cvt_pk_bf16_f32 v8, v2, v3
	v_cvt_pk_bf16_f32 v9, v4, v5
	global_store_dwordx4 v[18:19], v[6:9], off offset:256
	s_cbranch_vccz .LBB0_338
	s_waitcnt vmcnt(0)
	s_cmpk_gt_u32 s3, 0xff
	s_cbranch_scc1 .LBB0_349
	s_barrier
.LBB0_349:
	s_barrier
	s_setprio 0

.LBB0_355:
	s_ashr_i32 s0, s6, 3
	s_add_u32 s30, s56, 0x1d400000
	s_addc_u32 s31, s57, 0
	s_add_i32 s0, s7, s0
	s_ashr_i32 s6, s0, 31
	s_lshr_b32 s6, s6, 26
	s_add_i32 s6, s0, s6
	s_ashr_i32 s7, s6, 6
	s_andn2_b32 s6, s6, 63
	s_sub_i32 s6, s0, s6
	s_bfe_i32 s0, s6, 0x80000
	s_bfe_u32 s0, s0, 0x3000c
	s_add_i32 s8, s6, s0
	s_bfe_i32 s0, s8, 0x80000
	s_and_b32 s8, s8, 0xf8
	s_sub_i32 s6, s6, s8
	s_lshl_b32 s7, s7, 3
	s_sext_i32_i16 s0, s0
	s_sext_i32_i8 s6, s6
	s_lshr_b32 s1, s3, 8
	s_lshr_b32 s0, s0, 3
	s_add_i32 s42, s7, s6
	s_lshr_b32 s10, s3, 6
	s_ashr_i32 s43, s42, 31
	s_bfe_i64 s[8:9], s[0:1], 0x100000
	s_lshl_b32 s33, s10, 10
	s_lshl_b64 s[6:7], s[42:43], 20
	s_lshl_b64 s[8:9], s[8:9], 20
	s_add_u32 s46, s30, s8
	s_addc_u32 s47, s31, s9
	s_add_i32 s34, s33, 0
	s_add_i32 m0, s34, 0x10000
	v_mov_b32_e32 v133, 0
	global_load_lds_dwordx4 v132, s[46:47]
	s_add_i32 m0, s34, 0x12000
	s_add_u32 s44, s56, s6
	global_load_lds_dwordx4 v136, s[46:47]
	s_addc_u32 s45, s57, s7
	s_mov_b32 m0, s34
	s_add_i32 s35, s34, 0x2000
	global_load_lds_dwordx4 v130, s[44:45]
	s_mov_b32 m0, s35
	s_add_u32 s6, s46, 0x80000
	global_load_lds_dwordx4 v134, s[44:45]
	s_addc_u32 s7, s47, 0
	s_add_i32 m0, s34, 0x14000
	v_mov_b32_e32 v137, v133
	global_load_lds_dwordx4 v132, s[6:7]
	s_add_i32 m0, s34, 0x16000
	v_mov_b32_e32 v131, v133
	global_load_lds_dwordx4 v136, s[6:7]
	s_add_u32 s6, s44, 0x80000
	s_addc_u32 s7, s45, 0
	s_add_i32 s43, s34, 0x4000
	s_mov_b32 m0, s43
	s_add_i32 s60, s34, 0x6000
	global_load_lds_dwordx4 v130, s[6:7]
	s_mov_b32 m0, s60
	v_mov_b32_e32 v135, v133
	global_load_lds_dwordx4 v134, s[6:7]
	s_mov_b32 s61, 0
	v_lshl_add_u64 v[8:9], s[46:47], 0, v[132:133]
	v_lshl_add_u64 v[6:7], s[46:47], 0, v[136:137]
	v_lshl_add_u64 v[4:5], s[44:45], 0, v[130:131]
	v_lshl_add_u64 v[2:3], s[44:45], 0, v[134:135]
	s_cmp_lg_u32 s1, 1
	s_mov_b64 s[6:7], 0x80000
	s_cbranch_scc1 .LBB0_357
	s_setprio 1
	s_barrier

.LBB0_365:
	ds_read_b128 v[158:161], v150
	ds_read_b128 v[162:165], v150 offset:1024
	ds_read_b128 v[166:169], v150 offset:2048
	ds_read_b128 v[170:173], v150 offset:3072
	s_add_u32 s46, s44, 0xfff80080
	s_addc_u32 s47, s45, -1
	s_cmp_eq_u32 s76, 28
	s_cselect_b32 s51, s37, s47
	s_cselect_b32 s50, s72, s46
	s_cselect_b32 s47, s27, s75
	s_cselect_b32 s46, s73, s74
	v_lshl_add_u64 v[148:149], s[44:45], 0, v[138:139]
	s_add_i32 m0, s34, 0xc000
	ds_read_b128 v[174:177], v151
	ds_read_b128 v[178:181], v151 offset:1024
	ds_read_b128 v[182:185], v151 offset:2048
	ds_read_b128 v[186:189], v151 offset:3072
	ds_read_b128 v[190:193], v151 offset:4096
	ds_read_b128 v[194:197], v151 offset:5120
	ds_read_b128 v[204:207], v151 offset:6144
	ds_read_b128 v[208:211], v151 offset:7168
	global_load_lds_dwordx4 v[148:149], off
	v_lshl_add_u64 v[148:149], s[44:45], 0, v[140:141]
	s_add_i32 m0, s34, 0xe000
	s_nop 0
	global_load_lds_dwordx4 v[148:149], off
	s_waitcnt lgkmcnt(8)
	s_barrier
	s_waitcnt lgkmcnt(0)
	s_waitcnt lgkmcnt(0)
	v_mfma_f32_16x16x32_bf16 v[126:129], v[158:161], v[174:177], v[126:129]
	v_mfma_f32_16x16x32_bf16 v[122:125], v[166:169], v[174:177], v[122:125]
	v_mfma_f32_16x16x32_bf16 v[114:117], v[158:161], v[182:185], v[114:117]
	v_mfma_f32_16x16x32_bf16 v[106:109], v[166:169], v[182:185], v[106:109]
	v_mfma_f32_16x16x32_bf16 v[98:101], v[158:161], v[190:193], v[98:101]
	v_mfma_f32_16x16x32_bf16 v[90:93], v[166:169], v[190:193], v[90:93]
	v_mfma_f32_16x16x32_bf16 v[82:85], v[158:161], v[204:207], v[82:85]
	v_mfma_f32_16x16x32_bf16 v[74:77], v[166:169], v[204:207], v[74:77]
	v_mfma_f32_16x16x32_bf16 v[126:129], v[162:165], v[178:181], v[126:129]
	v_mfma_f32_16x16x32_bf16 v[122:125], v[170:173], v[178:181], v[122:125]
	v_mfma_f32_16x16x32_bf16 v[114:117], v[162:165], v[186:189], v[114:117]
	v_mfma_f32_16x16x32_bf16 v[106:109], v[170:173], v[186:189], v[106:109]
	v_mfma_f32_16x16x32_bf16 v[98:101], v[162:165], v[194:197], v[98:101]
	v_mfma_f32_16x16x32_bf16 v[90:93], v[170:173], v[194:197], v[90:93]
	v_mfma_f32_16x16x32_bf16 v[82:85], v[162:165], v[208:211], v[82:85]
	v_mfma_f32_16x16x32_bf16 v[74:77], v[170:173], v[208:211], v[74:77]
	s_barrier
	s_add_i32 s77, s65, s33
	v_lshl_add_u64 v[148:149], s[46:47], 0, v[132:133]
	s_mov_b32 m0, s77
	ds_read_b128 v[212:215], v152
	ds_read_b128 v[216:219], v152 offset:1024
	ds_read_b128 v[220:223], v152 offset:2048
	ds_read_b128 v[224:227], v152 offset:3072
	global_load_lds_dwordx4 v[148:149], off
	v_lshl_add_u64 v[198:199], s[46:47], 0, v[136:137]
	s_add_i32 m0, s77, 0x2000
	s_nop 0
	global_load_lds_dwordx4 v[198:199], off
	s_barrier
	s_waitcnt lgkmcnt(0)
	s_waitcnt lgkmcnt(0)
	v_mfma_f32_16x16x32_bf16 v[118:121], v[212:215], v[174:177], v[118:121]
	v_mfma_f32_16x16x32_bf16 v[110:113], v[220:223], v[174:177], v[110:113]
	v_mfma_f32_16x16x32_bf16 v[102:105], v[212:215], v[182:185], v[102:105]
	v_mfma_f32_16x16x32_bf16 v[94:97], v[220:223], v[182:185], v[94:97]
	v_mfma_f32_16x16x32_bf16 v[86:89], v[212:215], v[190:193], v[86:89]
	v_mfma_f32_16x16x32_bf16 v[78:81], v[220:223], v[190:193], v[78:81]
	v_mfma_f32_16x16x32_bf16 v[70:73], v[212:215], v[204:207], v[70:73]
	v_mfma_f32_16x16x32_bf16 v[66:69], v[220:223], v[204:207], v[66:69]
	v_mfma_f32_16x16x32_bf16 v[118:121], v[216:219], v[178:181], v[118:121]
	v_mfma_f32_16x16x32_bf16 v[110:113], v[224:227], v[178:181], v[110:113]
	v_mfma_f32_16x16x32_bf16 v[102:105], v[216:219], v[186:189], v[102:105]
	v_mfma_f32_16x16x32_bf16 v[94:97], v[224:227], v[186:189], v[94:97]
	v_mfma_f32_16x16x32_bf16 v[86:89], v[216:219], v[194:197], v[86:89]
	v_mfma_f32_16x16x32_bf16 v[78:81], v[224:227], v[194:197], v[78:81]
	v_mfma_f32_16x16x32_bf16 v[70:73], v[216:219], v[208:211], v[70:73]
	v_mfma_f32_16x16x32_bf16 v[66:69], v[224:227], v[208:211], v[66:69]
	s_mov_b32 m0, s34
	v_lshl_add_u64 v[228:229], s[50:51], 0, v[130:131]
	s_barrier
	ds_read_b128 v[174:177], v151 offset:16384
	ds_read_b128 v[178:181], v151 offset:17408
	ds_read_b128 v[182:185], v151 offset:18432
	ds_read_b128 v[186:189], v151 offset:19456
	ds_read_b128 v[190:193], v151 offset:20480
	ds_read_b128 v[194:197], v151 offset:21504
	ds_read_b128 v[204:207], v151 offset:22528
	ds_read_b128 v[208:211], v151 offset:23552
	global_load_lds_dwordx4 v[228:229], off
	v_lshl_add_u64 v[230:231], s[50:51], 0, v[134:135]
	s_mov_b32 m0, s35
	s_nop 0
	global_load_lds_dwordx4 v[230:231], off
	s_barrier
	s_waitcnt lgkmcnt(0)
	s_waitcnt lgkmcnt(0)
	v_mfma_f32_16x16x32_bf16 v[62:65], v[158:161], v[174:177], v[62:65]
	v_mfma_f32_16x16x32_bf16 v[58:61], v[166:169], v[174:177], v[58:61]
	v_mfma_f32_16x16x32_bf16 v[54:57], v[158:161], v[182:185], v[54:57]
	v_mfma_f32_16x16x32_bf16 v[46:49], v[166:169], v[182:185], v[46:49]
	v_mfma_f32_16x16x32_bf16 v[38:41], v[158:161], v[190:193], v[38:41]
	v_mfma_f32_16x16x32_bf16 v[30:33], v[166:169], v[190:193], v[30:33]
	v_mfma_f32_16x16x32_bf16 v[22:25], v[158:161], v[204:207], v[22:25]
	v_mfma_f32_16x16x32_bf16 v[14:17], v[166:169], v[204:207], v[14:17]
	v_mfma_f32_16x16x32_bf16 v[62:65], v[162:165], v[178:181], v[62:65]
	v_mfma_f32_16x16x32_bf16 v[58:61], v[170:173], v[178:181], v[58:61]
	v_mfma_f32_16x16x32_bf16 v[54:57], v[162:165], v[186:189], v[54:57]
	v_mfma_f32_16x16x32_bf16 v[46:49], v[170:173], v[186:189], v[46:49]
	v_mfma_f32_16x16x32_bf16 v[38:41], v[162:165], v[194:197], v[38:41]
	v_mfma_f32_16x16x32_bf16 v[30:33], v[170:173], v[194:197], v[30:33]
	v_mfma_f32_16x16x32_bf16 v[22:25], v[162:165], v[208:211], v[22:25]
	v_mfma_f32_16x16x32_bf16 v[14:17], v[170:173], v[208:211], v[14:17]
	s_barrier
	s_add_u32 s78, s46, 0x80000
	s_addc_u32 s79, s47, 0
	s_add_i32 s77, s66, s33
	v_lshl_add_u64 v[158:159], s[78:79], 0, v[132:133]
	s_mov_b32 m0, s77
	s_nop 0
	global_load_lds_dwordx4 v[158:159], off
	v_lshl_add_u64 v[158:159], s[78:79], 0, v[136:137]
	s_add_i32 m0, s77, 0x2000
	s_nop 0
	global_load_lds_dwordx4 v[158:159], off
	s_waitcnt vmcnt(6)
	s_barrier
	v_mfma_f32_16x16x32_bf16 v[50:53], v[212:215], v[174:177], v[50:53]
	v_mfma_f32_16x16x32_bf16 v[42:45], v[220:223], v[174:177], v[42:45]
	v_mfma_f32_16x16x32_bf16 v[34:37], v[212:215], v[182:185], v[34:37]
	v_mfma_f32_16x16x32_bf16 v[26:29], v[220:223], v[182:185], v[26:29]
	v_mfma_f32_16x16x32_bf16 v[18:21], v[212:215], v[190:193], v[18:21]
	v_mfma_f32_16x16x32_bf16 v[10:13], v[220:223], v[190:193], v[10:13]
	v_mfma_f32_16x16x32_bf16 v[6:9], v[212:215], v[204:207], v[6:9]
	v_mfma_f32_16x16x32_bf16 v[2:5], v[220:223], v[204:207], v[2:5]
	v_mfma_f32_16x16x32_bf16 v[50:53], v[216:219], v[178:181], v[50:53]
	v_mfma_f32_16x16x32_bf16 v[42:45], v[224:227], v[178:181], v[42:45]
	v_mfma_f32_16x16x32_bf16 v[34:37], v[216:219], v[186:189], v[34:37]
	v_mfma_f32_16x16x32_bf16 v[26:29], v[224:227], v[186:189], v[26:29]
	v_mfma_f32_16x16x32_bf16 v[18:21], v[216:219], v[194:197], v[18:21]
	v_mfma_f32_16x16x32_bf16 v[10:13], v[224:227], v[194:197], v[10:13]
	v_mfma_f32_16x16x32_bf16 v[6:9], v[216:219], v[208:211], v[6:9]
	v_mfma_f32_16x16x32_bf16 v[2:5], v[224:227], v[208:211], v[2:5]
	s_add_i32 s77, 0, 0x18000
	v_add_u32_e32 v153, s77, v155
	s_barrier
	ds_read_b128 v[158:161], v153
	ds_read_b128 v[162:165], v153 offset:1024
	ds_read_b128 v[166:169], v153 offset:2048
	ds_read_b128 v[170:173], v153 offset:3072
	s_add_u32 s50, s50, 0x80000
	s_addc_u32 s51, s51, 0
	s_mov_b32 m0, s43
	v_lshl_add_u64 v[212:213], s[50:51], 0, v[130:131]
	ds_read_b128 v[174:177], v151 offset:32768
	ds_read_b128 v[178:181], v151 offset:33792
	ds_read_b128 v[182:185], v151 offset:34816
	ds_read_b128 v[186:189], v151 offset:35840
	ds_read_b128 v[190:193], v151 offset:36864
	ds_read_b128 v[194:197], v151 offset:37888
	ds_read_b128 v[204:207], v151 offset:38912
	ds_read_b128 v[208:211], v151 offset:39936
	global_load_lds_dwordx4 v[212:213], off
	v_lshl_add_u64 v[212:213], s[50:51], 0, v[134:135]
	s_mov_b32 m0, s60
	s_nop 0
	global_load_lds_dwordx4 v[212:213], off
	s_waitcnt lgkmcnt(8)
	s_barrier
	s_waitcnt lgkmcnt(0)
	s_waitcnt lgkmcnt(0)
	v_mfma_f32_16x16x32_bf16 v[126:129], v[158:161], v[174:177], v[126:129]
	v_mfma_f32_16x16x32_bf16 v[122:125], v[166:169], v[174:177], v[122:125]
	v_mfma_f32_16x16x32_bf16 v[114:117], v[158:161], v[182:185], v[114:117]
	v_mfma_f32_16x16x32_bf16 v[106:109], v[166:169], v[182:185], v[106:109]
	v_mfma_f32_16x16x32_bf16 v[98:101], v[158:161], v[190:193], v[98:101]
	v_mfma_f32_16x16x32_bf16 v[90:93], v[166:169], v[190:193], v[90:93]
	v_mfma_f32_16x16x32_bf16 v[82:85], v[158:161], v[204:207], v[82:85]
	v_mfma_f32_16x16x32_bf16 v[74:77], v[166:169], v[204:207], v[74:77]
	v_mfma_f32_16x16x32_bf16 v[126:129], v[162:165], v[178:181], v[126:129]
	v_mfma_f32_16x16x32_bf16 v[122:125], v[170:173], v[178:181], v[122:125]
	v_mfma_f32_16x16x32_bf16 v[114:117], v[162:165], v[186:189], v[114:117]
	v_mfma_f32_16x16x32_bf16 v[106:109], v[170:173], v[186:189], v[106:109]
	v_mfma_f32_16x16x32_bf16 v[98:101], v[162:165], v[194:197], v[98:101]
	v_mfma_f32_16x16x32_bf16 v[90:93], v[170:173], v[194:197], v[90:93]
	v_mfma_f32_16x16x32_bf16 v[82:85], v[162:165], v[208:211], v[82:85]
	v_mfma_f32_16x16x32_bf16 v[74:77], v[170:173], v[208:211], v[74:77]
	s_barrier
	s_add_i32 s50, 0, 0x1c000
	s_add_i32 s51, s77, s33
	v_add_u32_e32 v153, s50, v155
	v_lshl_add_u64 v[148:149], v[148:149], 0, s[10:11]
	s_mov_b32 m0, s51
	ds_read_b128 v[212:215], v153
	ds_read_b128 v[216:219], v153 offset:1024
	ds_read_b128 v[220:223], v153 offset:2048
	ds_read_b128 v[224:227], v153 offset:3072
	global_load_lds_dwordx4 v[148:149], off
	v_lshl_add_u64 v[148:149], v[198:199], 0, s[10:11]
	s_add_i32 m0, s51, 0x2000
	s_nop 0
	global_load_lds_dwordx4 v[148:149], off
	s_barrier
	s_waitcnt lgkmcnt(0)
	s_waitcnt lgkmcnt(0)
	v_mfma_f32_16x16x32_bf16 v[118:121], v[212:215], v[174:177], v[118:121]
	v_mfma_f32_16x16x32_bf16 v[110:113], v[220:223], v[174:177], v[110:113]
	v_mfma_f32_16x16x32_bf16 v[102:105], v[212:215], v[182:185], v[102:105]
	v_mfma_f32_16x16x32_bf16 v[94:97], v[220:223], v[182:185], v[94:97]
	v_mfma_f32_16x16x32_bf16 v[86:89], v[212:215], v[190:193], v[86:89]
	v_mfma_f32_16x16x32_bf16 v[78:81], v[220:223], v[190:193], v[78:81]
	v_mfma_f32_16x16x32_bf16 v[70:73], v[212:215], v[204:207], v[70:73]
	v_mfma_f32_16x16x32_bf16 v[66:69], v[220:223], v[204:207], v[66:69]
	v_mfma_f32_16x16x32_bf16 v[118:121], v[216:219], v[178:181], v[118:121]
	v_mfma_f32_16x16x32_bf16 v[110:113], v[224:227], v[178:181], v[110:113]
	v_mfma_f32_16x16x32_bf16 v[102:105], v[216:219], v[186:189], v[102:105]
	v_mfma_f32_16x16x32_bf16 v[94:97], v[224:227], v[186:189], v[94:97]
	v_mfma_f32_16x16x32_bf16 v[86:89], v[216:219], v[194:197], v[86:89]
	v_mfma_f32_16x16x32_bf16 v[78:81], v[224:227], v[194:197], v[78:81]
	v_mfma_f32_16x16x32_bf16 v[70:73], v[216:219], v[208:211], v[70:73]
	v_mfma_f32_16x16x32_bf16 v[66:69], v[224:227], v[208:211], v[66:69]
	s_mov_b32 m0, s62
	v_lshl_add_u64 v[148:149], v[228:229], 0, s[10:11]
	s_barrier
	ds_read_b128 v[174:177], v151 offset:49152
	ds_read_b128 v[178:181], v151 offset:50176
	ds_read_b128 v[182:185], v151 offset:51200
	ds_read_b128 v[186:189], v151 offset:52224
	ds_read_b128 v[190:193], v151 offset:53248
	ds_read_b128 v[194:197], v151 offset:54272
	ds_read_b128 v[204:207], v151 offset:55296
	ds_read_b128 v[208:211], v151 offset:56320
	global_load_lds_dwordx4 v[148:149], off
	v_lshl_add_u64 v[148:149], v[230:231], 0, s[10:11]
	s_mov_b32 m0, s63
	s_nop 0
	global_load_lds_dwordx4 v[148:149], off
	s_barrier
	s_waitcnt lgkmcnt(0)
	s_waitcnt lgkmcnt(0)
	v_mfma_f32_16x16x32_bf16 v[62:65], v[158:161], v[174:177], v[62:65]
	v_mfma_f32_16x16x32_bf16 v[58:61], v[166:169], v[174:177], v[58:61]
	v_mfma_f32_16x16x32_bf16 v[54:57], v[158:161], v[182:185], v[54:57]
	v_mfma_f32_16x16x32_bf16 v[46:49], v[166:169], v[182:185], v[46:49]
	v_mfma_f32_16x16x32_bf16 v[38:41], v[158:161], v[190:193], v[38:41]
	v_mfma_f32_16x16x32_bf16 v[30:33], v[166:169], v[190:193], v[30:33]
	v_mfma_f32_16x16x32_bf16 v[22:25], v[158:161], v[204:207], v[22:25]
	v_mfma_f32_16x16x32_bf16 v[14:17], v[166:169], v[204:207], v[14:17]
	v_mfma_f32_16x16x32_bf16 v[62:65], v[162:165], v[178:181], v[62:65]
	v_mfma_f32_16x16x32_bf16 v[58:61], v[170:173], v[178:181], v[58:61]
	v_mfma_f32_16x16x32_bf16 v[54:57], v[162:165], v[186:189], v[54:57]
	v_mfma_f32_16x16x32_bf16 v[46:49], v[170:173], v[186:189], v[46:49]
	v_mfma_f32_16x16x32_bf16 v[38:41], v[162:165], v[194:197], v[38:41]
	v_mfma_f32_16x16x32_bf16 v[30:33], v[170:173], v[194:197], v[30:33]
	v_mfma_f32_16x16x32_bf16 v[22:25], v[162:165], v[208:211], v[22:25]
	v_mfma_f32_16x16x32_bf16 v[14:17], v[170:173], v[208:211], v[14:17]
	s_barrier
	s_add_u32 s46, s46, 0x80080
	s_addc_u32 s47, s47, 0
	s_add_i32 s50, s50, s33
	v_lshl_add_u64 v[148:149], s[46:47], 0, v[132:133]
	s_mov_b32 m0, s50
	s_nop 0
	global_load_lds_dwordx4 v[148:149], off
	v_lshl_add_u64 v[148:149], s[46:47], 0, v[136:137]
	s_add_i32 m0, s50, 0x2000
	s_nop 0
	global_load_lds_dwordx4 v[148:149], off
	s_waitcnt vmcnt(6)
	s_barrier
	v_mfma_f32_16x16x32_bf16 v[50:53], v[212:215], v[174:177], v[50:53]
	v_mfma_f32_16x16x32_bf16 v[42:45], v[220:223], v[174:177], v[42:45]
	v_mfma_f32_16x16x32_bf16 v[34:37], v[212:215], v[182:185], v[34:37]
	v_mfma_f32_16x16x32_bf16 v[26:29], v[220:223], v[182:185], v[26:29]
	v_mfma_f32_16x16x32_bf16 v[18:21], v[212:215], v[190:193], v[18:21]
	v_mfma_f32_16x16x32_bf16 v[10:13], v[220:223], v[190:193], v[10:13]
	v_mfma_f32_16x16x32_bf16 v[6:9], v[212:215], v[204:207], v[6:9]
	v_mfma_f32_16x16x32_bf16 v[2:5], v[220:223], v[204:207], v[2:5]
	v_mfma_f32_16x16x32_bf16 v[50:53], v[216:219], v[178:181], v[50:53]
	v_mfma_f32_16x16x32_bf16 v[42:45], v[224:227], v[178:181], v[42:45]
	v_mfma_f32_16x16x32_bf16 v[34:37], v[216:219], v[186:189], v[34:37]
	v_mfma_f32_16x16x32_bf16 v[26:29], v[224:227], v[186:189], v[26:29]
	v_mfma_f32_16x16x32_bf16 v[18:21], v[216:219], v[194:197], v[18:21]
	v_mfma_f32_16x16x32_bf16 v[10:13], v[224:227], v[194:197], v[10:13]
	v_mfma_f32_16x16x32_bf16 v[6:9], v[216:219], v[208:211], v[6:9]
	v_mfma_f32_16x16x32_bf16 v[2:5], v[224:227], v[208:211], v[2:5]
	s_add_i32 s76, s76, 2
	s_add_u32 s44, s44, 0x100
	s_addc_u32 s45, s45, 0
	s_add_u32 s74, s74, 0x100
	s_addc_u32 s75, s75, 0
	s_cmp_gt_u32 s76, 29
	s_barrier
	s_cbranch_scc0 .LBB0_365
	v_lshl_add_u32 v158, s42, 8, v157
	v_lshl_or_b32 v148, s71, 8, v154
	v_ashrrev_i32_e32 v159, 31, v158
	v_ashrrev_i32_e32 v149, 31, v148
	v_lshlrev_b64 v[160:161], 12, v[158:159]
	v_lshl_add_u64 v[160:161], s[8:9], 0, v[160:161]
	v_lshlrev_b64 v[162:163], 1, v[148:149]
	v_lshl_add_u64 v[148:149], v[160:161], 0, v[162:163]
	v_cvt_pk_bf16_f32 v126, v126, v127
	v_cvt_pk_bf16_f32 v127, v128, v129
	v_cvt_pk_bf16_f32 v128, v122, v123
	v_cvt_pk_bf16_f32 v129, v124, v125
	global_store_dwordx4 v[148:149], v[126:129], off
	v_cvt_pk_bf16_f32 v118, v118, v119
	v_cvt_pk_bf16_f32 v119, v120, v121
	v_cvt_pk_bf16_f32 v120, v110, v111
	v_or_b32_e32 v110, 16, v158
	v_ashrrev_i32_e32 v111, 31, v110
	v_lshlrev_b64 v[110:111], 12, v[110:111]
	v_lshl_add_u64 v[110:111], s[8:9], 0, v[110:111]
	v_cvt_pk_bf16_f32 v121, v112, v113
	global_store_dwordx4 v[148:149], v[118:121], off offset:256
	s_mov_b32 s71, s26
	s_mov_b32 s42, s36
	v_lshl_add_u64 v[118:119], v[110:111], 0, v[162:163]
	v_cvt_pk_bf16_f32 v110, v114, v115
	v_cvt_pk_bf16_f32 v111, v116, v117
	v_cvt_pk_bf16_f32 v112, v106, v107
	v_cvt_pk_bf16_f32 v113, v108, v109
	global_store_dwordx4 v[118:119], v[110:113], off
	v_cvt_pk_bf16_f32 v102, v102, v103
	v_cvt_pk_bf16_f32 v103, v104, v105
	v_cvt_pk_bf16_f32 v104, v94, v95
	v_or_b32_e32 v94, 32, v158
	v_ashrrev_i32_e32 v95, 31, v94
	v_lshlrev_b64 v[94:95], 12, v[94:95]
	v_lshl_add_u64 v[94:95], s[8:9], 0, v[94:95]
	v_cvt_pk_bf16_f32 v105, v96, v97
	global_store_dwordx4 v[118:119], v[102:105], off offset:256
	s_mov_b64 s[46:47], s[40:41]
	s_mov_b64 s[44:45], s[38:39]
	v_lshl_add_u64 v[102:103], v[94:95], 0, v[162:163]
	v_cvt_pk_bf16_f32 v94, v98, v99
	v_cvt_pk_bf16_f32 v95, v100, v101
	v_cvt_pk_bf16_f32 v96, v90, v91
	v_cvt_pk_bf16_f32 v97, v92, v93
	global_store_dwordx4 v[102:103], v[94:97], off
	v_cvt_pk_bf16_f32 v86, v86, v87
	v_cvt_pk_bf16_f32 v87, v88, v89
	v_cvt_pk_bf16_f32 v88, v78, v79
	v_or_b32_e32 v78, 48, v158
	v_ashrrev_i32_e32 v79, 31, v78
	v_lshlrev_b64 v[78:79], 12, v[78:79]
	v_lshl_add_u64 v[78:79], s[8:9], 0, v[78:79]
	v_cvt_pk_bf16_f32 v89, v80, v81
	global_store_dwordx4 v[102:103], v[86:89], off offset:256
	s_nop 1
	v_lshl_add_u64 v[86:87], v[78:79], 0, v[162:163]
	v_cvt_pk_bf16_f32 v78, v82, v83
	v_cvt_pk_bf16_f32 v79, v84, v85
	v_cvt_pk_bf16_f32 v80, v74, v75
	v_cvt_pk_bf16_f32 v81, v76, v77
	global_store_dwordx4 v[86:87], v[78:81], off
	v_cvt_pk_bf16_f32 v70, v70, v71
	v_cvt_pk_bf16_f32 v71, v72, v73
	v_cvt_pk_bf16_f32 v72, v66, v67
	v_cvt_pk_bf16_f32 v73, v68, v69
	global_store_dwordx4 v[86:87], v[70:73], off offset:256
	v_cvt_pk_bf16_f32 v62, v62, v63
	v_cvt_pk_bf16_f32 v63, v64, v65
	v_cvt_pk_bf16_f32 v64, v58, v59
	v_add_co_u32_e32 v58, vcc, s67, v148
	v_lshl_add_u64 v[66:67], v[148:149], 0, s[6:7]
	s_nop 0
	v_addc_co_u32_e32 v59, vcc, 0, v149, vcc
	v_cvt_pk_bf16_f32 v65, v60, v61
	global_store_dwordx4 v[58:59], v[62:65], off
	v_cvt_pk_bf16_f32 v50, v50, v51
	v_cvt_pk_bf16_f32 v51, v52, v53
	v_cvt_pk_bf16_f32 v52, v42, v43
	v_cvt_pk_bf16_f32 v53, v44, v45
	global_store_dwordx4 v[66:67], v[50:53], off offset:256
	v_cvt_pk_bf16_f32 v42, v54, v55
	v_cvt_pk_bf16_f32 v43, v56, v57
	v_cvt_pk_bf16_f32 v44, v46, v47
	v_add_co_u32_e32 v46, vcc, s68, v148
	s_nop 0
	v_lshl_add_u64 v[50:51], v[148:149], 0, s[16:17]
	v_addc_co_u32_e32 v47, vcc, 0, v149, vcc
	v_cvt_pk_bf16_f32 v45, v48, v49
	global_store_dwordx4 v[46:47], v[42:45], off
	v_cvt_pk_bf16_f32 v34, v34, v35
	v_cvt_pk_bf16_f32 v35, v36, v37
	v_cvt_pk_bf16_f32 v36, v26, v27
	v_cvt_pk_bf16_f32 v37, v28, v29
	global_store_dwordx4 v[50:51], v[34:37], off offset:256
	v_cvt_pk_bf16_f32 v26, v38, v39
	v_cvt_pk_bf16_f32 v27, v40, v41
	v_cvt_pk_bf16_f32 v28, v30, v31
	v_add_co_u32_e32 v30, vcc, s69, v148
	s_nop 0
	v_lshl_add_u64 v[34:35], v[148:149], 0, s[18:19]
	v_addc_co_u32_e32 v31, vcc, 0, v149, vcc
	v_cvt_pk_bf16_f32 v29, v32, v33
	global_store_dwordx4 v[30:31], v[26:29], off
	v_cvt_pk_bf16_f32 v18, v18, v19
	v_cvt_pk_bf16_f32 v19, v20, v21
	v_cvt_pk_bf16_f32 v20, v10, v11
	v_cvt_pk_bf16_f32 v21, v12, v13
	global_store_dwordx4 v[34:35], v[18:21], off offset:256
	v_cvt_pk_bf16_f32 v10, v22, v23
	v_cvt_pk_bf16_f32 v11, v24, v25
	v_cvt_pk_bf16_f32 v12, v14, v15
	v_add_co_u32_e32 v14, vcc, s70, v148
	s_nop 0
	v_lshl_add_u64 v[18:19], v[148:149], 0, s[24:25]
	v_addc_co_u32_e32 v15, vcc, 0, v149, vcc
	s_and_b64 vcc, exec, s[0:1]
	v_cvt_pk_bf16_f32 v13, v16, v17
	global_store_dwordx4 v[14:15], v[10:13], off
	v_cvt_pk_bf16_f32 v6, v6, v7
	v_cvt_pk_bf16_f32 v7, v8, v9
	v_cvt_pk_bf16_f32 v8, v2, v3
	v_cvt_pk_bf16_f32 v9, v4, v5
	global_store_dwordx4 v[18:19], v[6:9], off offset:256
	s_cbranch_vccz .LBB0_358
	s_waitcnt vmcnt(0)
	s_cmpk_gt_u32 s3, 0xff
	s_cbranch_scc1 .LBB0_369
	s_barrier

.LBB0_899:
	v_lshrrev_b32_e32 v3, 1, v10
	v_and_b32_e32 v14, 24, v3
	v_lshrrev_b32_e32 v3, 5, v10
	s_add_u32 s30, s56, 0x1dc00000
	v_and_b32_e32 v3, 4, v3
	v_bfe_u32 v4, v10, 2, 2
	s_addc_u32 s31, s57, 0
	v_lshlrev_b32_e32 v1, 4, v10
	v_and_b32_e32 v2, 32, v10
	v_bfe_u32 v13, v10, 2, 4
	v_or3_b32 v3, v3, v4, v14
	v_lshrrev_b32_e32 v4, 3, v10
	s_movk_i32 s7, 0x70
	s_add_i32 s0, s6, s0
	v_bitop3_b32 v11, v1, v2, 48 bitop3:0x6c
	v_and_b32_e32 v12, 64, v10
	v_and_or_b32 v5, v4, s7, v13
	s_movk_i32 s7, 0x60
	v_add_u32_e32 v15, 0x2000, v1
	s_ashr_i32 s6, s0, 31
	v_or_b32_e32 v2, v11, v12
	v_and_or_b32 v4, v4, s7, v3
	v_lshrrev_b32_e32 v1, 7, v15
	s_movk_i32 s7, 0xf0
	s_lshr_b32 s6, s6, 26
	v_lshl_or_b32 v132, v4, 12, v2
	v_and_or_b32 v4, v1, s7, v13
	s_movk_i32 s7, 0xe0
	s_add_i32 s6, s0, s6
	v_and_or_b32 v1, v1, s7, v3
	s_ashr_i32 s7, s6, 6
	s_and_b32 s6, s6, 0xffc0
	s_sub_i32 s6, s0, s6
	s_bfe_i32 s0, s6, 0x80000
	s_bfe_u32 s0, s0, 0x3000c
	s_add_i32 s8, s6, s0
	s_bfe_i32 s0, s8, 0x80000
	s_and_b32 s8, s8, 0xf8
	s_sub_i32 s6, s6, s8
	s_lshl_b32 s7, s7, 3
	s_sext_i32_i16 s0, s0
	s_sext_i32_i8 s6, s6
	s_lshr_b32 s1, s3, 8
	s_lshr_b32 s0, s0, 3
	s_add_i32 s38, s7, s6
	s_lshr_b32 s10, s3, 6
	s_ashr_i32 s39, s38, 31
	s_bfe_i64 s[8:9], s[0:1], 0x100000
	s_lshl_b32 s33, s10, 10
	s_lshl_b64 s[6:7], s[38:39], 20
	s_lshl_b64 s[8:9], s[8:9], 20
	s_add_u32 s42, s30, s8
	s_addc_u32 s43, s31, s9
	s_add_i32 s34, s33, 0
	s_add_i32 m0, s34, 0x10000
	v_lshl_or_b32 v136, v1, 12, v2
	global_load_lds_dwordx4 v132, s[42:43]
	s_add_i32 m0, s34, 0x12000
	s_add_u32 s40, s56, s6
	v_lshl_or_b32 v130, v5, 12, v2
	global_load_lds_dwordx4 v136, s[42:43]
	s_addc_u32 s41, s57, s7
	s_mov_b32 m0, s34
	s_add_i32 s35, s34, 0x2000
	v_lshl_or_b32 v134, v4, 12, v2
	global_load_lds_dwordx4 v130, s[40:41]
	s_mov_b32 m0, s35
	s_add_u32 s6, s42, 0x80000
	global_load_lds_dwordx4 v134, s[40:41]
	s_addc_u32 s7, s43, 0
	s_add_i32 m0, s34, 0x14000
	v_mov_b32_e32 v133, 0
	global_load_lds_dwordx4 v132, s[6:7]
	s_add_i32 m0, s34, 0x16000
	v_mov_b32_e32 v137, v133
	global_load_lds_dwordx4 v136, s[6:7]
	s_add_u32 s6, s40, 0x80000
	s_addc_u32 s7, s41, 0
	s_add_i32 s39, s34, 0x4000
	s_mov_b32 m0, s39
	s_add_i32 s46, s34, 0x6000
	global_load_lds_dwordx4 v130, s[6:7]
	s_mov_b32 m0, s46
	v_mov_b32_e32 v131, v133
	global_load_lds_dwordx4 v134, s[6:7]
	v_mov_b32_e32 v135, v133
	s_mov_b32 s47, 0
	v_lshl_add_u64 v[8:9], s[42:43], 0, v[132:133]
	v_lshl_add_u64 v[6:7], s[42:43], 0, v[136:137]
	v_lshl_add_u64 v[4:5], s[40:41], 0, v[130:131]
	v_lshl_add_u64 v[2:3], s[40:41], 0, v[134:135]
	s_cmp_lg_u32 s1, 1
	s_mov_b64 s[6:7], 0x80000
	s_cbranch_scc1 .LBB0_901
	s_setprio 1
	s_barrier

.LBB0_909:
	ds_read_b128 v[154:157], v151
	ds_read_b128 v[158:161], v151 offset:1024
	ds_read_b128 v[162:165], v151 offset:2048
	ds_read_b128 v[166:169], v151 offset:3072
	s_add_u32 s42, s40, 0xfff80080
	s_addc_u32 s43, s41, -1
	s_cmp_eq_u32 s70, 28
	s_cselect_b32 s45, s25, s43
	s_cselect_b32 s44, s66, s42
	s_cselect_b32 s43, s23, s69
	s_cselect_b32 s42, s67, s68
	v_lshl_add_u64 v[148:149], s[40:41], 0, v[138:139]
	s_add_i32 m0, s34, 0xc000
	ds_read_b128 v[170:173], v152
	ds_read_b128 v[174:177], v152 offset:1024
	ds_read_b128 v[178:181], v152 offset:2048
	ds_read_b128 v[182:185], v152 offset:3072
	ds_read_b128 v[186:189], v152 offset:4096
	ds_read_b128 v[190:193], v152 offset:5120
	ds_read_b128 v[194:197], v152 offset:6144
	ds_read_b128 v[198:201], v152 offset:7168
	global_load_lds_dwordx4 v[148:149], off
	v_lshl_add_u64 v[148:149], s[40:41], 0, v[140:141]
	s_add_i32 m0, s34, 0xe000
	s_nop 0
	global_load_lds_dwordx4 v[148:149], off
	s_waitcnt lgkmcnt(8)
	s_barrier
	s_waitcnt lgkmcnt(0)
	s_waitcnt lgkmcnt(0)
	v_mfma_f32_16x16x32_bf16 v[126:129], v[154:157], v[170:173], v[126:129]
	v_mfma_f32_16x16x32_bf16 v[122:125], v[162:165], v[170:173], v[122:125]
	v_mfma_f32_16x16x32_bf16 v[114:117], v[154:157], v[178:181], v[114:117]
	v_mfma_f32_16x16x32_bf16 v[106:109], v[162:165], v[178:181], v[106:109]
	v_mfma_f32_16x16x32_bf16 v[98:101], v[154:157], v[186:189], v[98:101]
	v_mfma_f32_16x16x32_bf16 v[90:93], v[162:165], v[186:189], v[90:93]
	v_mfma_f32_16x16x32_bf16 v[82:85], v[154:157], v[194:197], v[82:85]
	v_mfma_f32_16x16x32_bf16 v[74:77], v[162:165], v[194:197], v[74:77]
	v_mfma_f32_16x16x32_bf16 v[126:129], v[158:161], v[174:177], v[126:129]
	v_mfma_f32_16x16x32_bf16 v[122:125], v[166:169], v[174:177], v[122:125]
	v_mfma_f32_16x16x32_bf16 v[114:117], v[158:161], v[182:185], v[114:117]
	v_mfma_f32_16x16x32_bf16 v[106:109], v[166:169], v[182:185], v[106:109]
	v_mfma_f32_16x16x32_bf16 v[98:101], v[158:161], v[190:193], v[98:101]
	v_mfma_f32_16x16x32_bf16 v[90:93], v[166:169], v[190:193], v[90:93]
	v_mfma_f32_16x16x32_bf16 v[82:85], v[158:161], v[198:201], v[82:85]
	v_mfma_f32_16x16x32_bf16 v[74:77], v[166:169], v[198:201], v[74:77]
	s_barrier
	s_add_i32 s71, s51, s33
	v_lshl_add_u64 v[148:149], s[42:43], 0, v[132:133]
	s_mov_b32 m0, s71
	ds_read_b128 v[202:205], v153
	ds_read_b128 v[206:209], v153 offset:1024
	ds_read_b128 v[210:213], v153 offset:2048
	ds_read_b128 v[214:217], v153 offset:3072
	global_load_lds_dwordx4 v[148:149], off
	v_lshl_add_u64 v[218:219], s[42:43], 0, v[136:137]
	s_add_i32 m0, s71, 0x2000
	s_nop 0
	global_load_lds_dwordx4 v[218:219], off
	s_barrier
	s_waitcnt lgkmcnt(0)
	s_waitcnt lgkmcnt(0)
	v_mfma_f32_16x16x32_bf16 v[118:121], v[202:205], v[170:173], v[118:121]
	v_mfma_f32_16x16x32_bf16 v[110:113], v[210:213], v[170:173], v[110:113]
	v_mfma_f32_16x16x32_bf16 v[102:105], v[202:205], v[178:181], v[102:105]
	v_mfma_f32_16x16x32_bf16 v[94:97], v[210:213], v[178:181], v[94:97]
	v_mfma_f32_16x16x32_bf16 v[86:89], v[202:205], v[186:189], v[86:89]
	v_mfma_f32_16x16x32_bf16 v[78:81], v[210:213], v[186:189], v[78:81]
	v_mfma_f32_16x16x32_bf16 v[70:73], v[202:205], v[194:197], v[70:73]
	v_mfma_f32_16x16x32_bf16 v[66:69], v[210:213], v[194:197], v[66:69]
	v_mfma_f32_16x16x32_bf16 v[118:121], v[206:209], v[174:177], v[118:121]
	v_mfma_f32_16x16x32_bf16 v[110:113], v[214:217], v[174:177], v[110:113]
	v_mfma_f32_16x16x32_bf16 v[102:105], v[206:209], v[182:185], v[102:105]
	v_mfma_f32_16x16x32_bf16 v[94:97], v[214:217], v[182:185], v[94:97]
	v_mfma_f32_16x16x32_bf16 v[86:89], v[206:209], v[190:193], v[86:89]
	v_mfma_f32_16x16x32_bf16 v[78:81], v[214:217], v[190:193], v[78:81]
	v_mfma_f32_16x16x32_bf16 v[70:73], v[206:209], v[198:201], v[70:73]
	v_mfma_f32_16x16x32_bf16 v[66:69], v[214:217], v[198:201], v[66:69]
	s_mov_b32 m0, s34
	v_lshl_add_u64 v[220:221], s[44:45], 0, v[130:131]
	s_barrier
	ds_read_b128 v[170:173], v152 offset:16384
	ds_read_b128 v[174:177], v152 offset:17408
	ds_read_b128 v[178:181], v152 offset:18432
	ds_read_b128 v[182:185], v152 offset:19456
	ds_read_b128 v[186:189], v152 offset:20480
	ds_read_b128 v[190:193], v152 offset:21504
	ds_read_b128 v[194:197], v152 offset:22528
	ds_read_b128 v[198:201], v152 offset:23552
	global_load_lds_dwordx4 v[220:221], off
	v_lshl_add_u64 v[222:223], s[44:45], 0, v[134:135]
	s_mov_b32 m0, s35
	s_nop 0
	global_load_lds_dwordx4 v[222:223], off
	s_barrier
	s_waitcnt lgkmcnt(0)
	s_waitcnt lgkmcnt(0)
	v_mfma_f32_16x16x32_bf16 v[62:65], v[154:157], v[170:173], v[62:65]
	v_mfma_f32_16x16x32_bf16 v[58:61], v[162:165], v[170:173], v[58:61]
	v_mfma_f32_16x16x32_bf16 v[54:57], v[154:157], v[178:181], v[54:57]
	v_mfma_f32_16x16x32_bf16 v[46:49], v[162:165], v[178:181], v[46:49]
	v_mfma_f32_16x16x32_bf16 v[38:41], v[154:157], v[186:189], v[38:41]
	v_mfma_f32_16x16x32_bf16 v[30:33], v[162:165], v[186:189], v[30:33]
	v_mfma_f32_16x16x32_bf16 v[22:25], v[154:157], v[194:197], v[22:25]
	v_mfma_f32_16x16x32_bf16 v[14:17], v[162:165], v[194:197], v[14:17]
	v_mfma_f32_16x16x32_bf16 v[62:65], v[158:161], v[174:177], v[62:65]
	v_mfma_f32_16x16x32_bf16 v[58:61], v[166:169], v[174:177], v[58:61]
	v_mfma_f32_16x16x32_bf16 v[54:57], v[158:161], v[182:185], v[54:57]
	v_mfma_f32_16x16x32_bf16 v[46:49], v[166:169], v[182:185], v[46:49]
	v_mfma_f32_16x16x32_bf16 v[38:41], v[158:161], v[190:193], v[38:41]
	v_mfma_f32_16x16x32_bf16 v[30:33], v[166:169], v[190:193], v[30:33]
	v_mfma_f32_16x16x32_bf16 v[22:25], v[158:161], v[198:201], v[22:25]
	v_mfma_f32_16x16x32_bf16 v[14:17], v[166:169], v[198:201], v[14:17]
	s_barrier
	s_add_u32 s72, s42, 0x80000
	s_addc_u32 s73, s43, 0
	s_add_i32 s71, s60, s33
	v_lshl_add_u64 v[154:155], s[72:73], 0, v[132:133]
	s_mov_b32 m0, s71
	s_nop 0
	global_load_lds_dwordx4 v[154:155], off
	v_lshl_add_u64 v[154:155], s[72:73], 0, v[136:137]
	s_add_i32 m0, s71, 0x2000
	s_nop 0
	global_load_lds_dwordx4 v[154:155], off
	s_waitcnt vmcnt(6)
	s_barrier
	v_mfma_f32_16x16x32_bf16 v[50:53], v[202:205], v[170:173], v[50:53]
	v_mfma_f32_16x16x32_bf16 v[42:45], v[210:213], v[170:173], v[42:45]
	v_mfma_f32_16x16x32_bf16 v[34:37], v[202:205], v[178:181], v[34:37]
	v_mfma_f32_16x16x32_bf16 v[26:29], v[210:213], v[178:181], v[26:29]
	v_mfma_f32_16x16x32_bf16 v[18:21], v[202:205], v[186:189], v[18:21]
	v_mfma_f32_16x16x32_bf16 v[10:13], v[210:213], v[186:189], v[10:13]
	v_mfma_f32_16x16x32_bf16 v[6:9], v[202:205], v[194:197], v[6:9]
	v_mfma_f32_16x16x32_bf16 v[2:5], v[210:213], v[194:197], v[2:5]
	v_mfma_f32_16x16x32_bf16 v[50:53], v[206:209], v[174:177], v[50:53]
	v_mfma_f32_16x16x32_bf16 v[42:45], v[214:217], v[174:177], v[42:45]
	v_mfma_f32_16x16x32_bf16 v[34:37], v[206:209], v[182:185], v[34:37]
	v_mfma_f32_16x16x32_bf16 v[26:29], v[214:217], v[182:185], v[26:29]
	v_mfma_f32_16x16x32_bf16 v[18:21], v[206:209], v[190:193], v[18:21]
	v_mfma_f32_16x16x32_bf16 v[10:13], v[214:217], v[190:193], v[10:13]
	v_mfma_f32_16x16x32_bf16 v[6:9], v[206:209], v[198:201], v[6:9]
	v_mfma_f32_16x16x32_bf16 v[2:5], v[214:217], v[198:201], v[2:5]
	s_add_i32 s71, 0, 0x18000
	v_add_u32_e32 v166, s71, v147
	s_barrier
	ds_read_b128 v[154:157], v166
	ds_read_b128 v[158:161], v166 offset:1024
	ds_read_b128 v[162:165], v166 offset:2048
	ds_read_b128 v[166:169], v166 offset:3072
	s_add_u32 s44, s44, 0x80000
	s_addc_u32 s45, s45, 0
	s_mov_b32 m0, s39
	v_lshl_add_u64 v[202:203], s[44:45], 0, v[130:131]
	ds_read_b128 v[170:173], v152 offset:32768
	ds_read_b128 v[174:177], v152 offset:33792
	ds_read_b128 v[178:181], v152 offset:34816
	ds_read_b128 v[182:185], v152 offset:35840
	ds_read_b128 v[186:189], v152 offset:36864
	ds_read_b128 v[190:193], v152 offset:37888
	ds_read_b128 v[194:197], v152 offset:38912
	ds_read_b128 v[198:201], v152 offset:39936
	global_load_lds_dwordx4 v[202:203], off
	v_lshl_add_u64 v[202:203], s[44:45], 0, v[134:135]
	s_mov_b32 m0, s46
	s_nop 0
	global_load_lds_dwordx4 v[202:203], off
	s_waitcnt lgkmcnt(8)
	s_barrier
	s_waitcnt lgkmcnt(0)
	s_waitcnt lgkmcnt(0)
	v_mfma_f32_16x16x32_bf16 v[126:129], v[154:157], v[170:173], v[126:129]
	v_mfma_f32_16x16x32_bf16 v[122:125], v[162:165], v[170:173], v[122:125]
	v_mfma_f32_16x16x32_bf16 v[114:117], v[154:157], v[178:181], v[114:117]
	v_mfma_f32_16x16x32_bf16 v[106:109], v[162:165], v[178:181], v[106:109]
	v_mfma_f32_16x16x32_bf16 v[98:101], v[154:157], v[186:189], v[98:101]
	v_mfma_f32_16x16x32_bf16 v[90:93], v[162:165], v[186:189], v[90:93]
	v_mfma_f32_16x16x32_bf16 v[82:85], v[154:157], v[194:197], v[82:85]
	v_mfma_f32_16x16x32_bf16 v[74:77], v[162:165], v[194:197], v[74:77]
	v_mfma_f32_16x16x32_bf16 v[126:129], v[158:161], v[174:177], v[126:129]
	v_mfma_f32_16x16x32_bf16 v[122:125], v[166:169], v[174:177], v[122:125]
	v_mfma_f32_16x16x32_bf16 v[114:117], v[158:161], v[182:185], v[114:117]
	v_mfma_f32_16x16x32_bf16 v[106:109], v[166:169], v[182:185], v[106:109]
	v_mfma_f32_16x16x32_bf16 v[98:101], v[158:161], v[190:193], v[98:101]
	v_mfma_f32_16x16x32_bf16 v[90:93], v[166:169], v[190:193], v[90:93]
	v_mfma_f32_16x16x32_bf16 v[82:85], v[158:161], v[198:201], v[82:85]
	v_mfma_f32_16x16x32_bf16 v[74:77], v[166:169], v[198:201], v[74:77]
	s_barrier
	s_add_i32 s44, 0, 0x1c000
	s_add_i32 s45, s71, s33
	v_add_u32_e32 v214, s44, v147
	v_lshl_add_u64 v[148:149], v[148:149], 0, s[10:11]
	s_mov_b32 m0, s45
	ds_read_b128 v[202:205], v214
	ds_read_b128 v[206:209], v214 offset:1024
	ds_read_b128 v[210:213], v214 offset:2048
	ds_read_b128 v[214:217], v214 offset:3072
	global_load_lds_dwordx4 v[148:149], off
	v_lshl_add_u64 v[148:149], v[218:219], 0, s[10:11]
	s_add_i32 m0, s45, 0x2000
	s_nop 0
	global_load_lds_dwordx4 v[148:149], off
	s_barrier
	s_waitcnt lgkmcnt(0)
	s_waitcnt lgkmcnt(0)
	v_mfma_f32_16x16x32_bf16 v[118:121], v[202:205], v[170:173], v[118:121]
	v_mfma_f32_16x16x32_bf16 v[110:113], v[210:213], v[170:173], v[110:113]
	v_mfma_f32_16x16x32_bf16 v[102:105], v[202:205], v[178:181], v[102:105]
	v_mfma_f32_16x16x32_bf16 v[94:97], v[210:213], v[178:181], v[94:97]
	v_mfma_f32_16x16x32_bf16 v[86:89], v[202:205], v[186:189], v[86:89]
	v_mfma_f32_16x16x32_bf16 v[78:81], v[210:213], v[186:189], v[78:81]
	v_mfma_f32_16x16x32_bf16 v[70:73], v[202:205], v[194:197], v[70:73]
	v_mfma_f32_16x16x32_bf16 v[66:69], v[210:213], v[194:197], v[66:69]
	v_mfma_f32_16x16x32_bf16 v[118:121], v[206:209], v[174:177], v[118:121]
	v_mfma_f32_16x16x32_bf16 v[110:113], v[214:217], v[174:177], v[110:113]
	v_mfma_f32_16x16x32_bf16 v[102:105], v[206:209], v[182:185], v[102:105]
	v_mfma_f32_16x16x32_bf16 v[94:97], v[214:217], v[182:185], v[94:97]
	v_mfma_f32_16x16x32_bf16 v[86:89], v[206:209], v[190:193], v[86:89]
	v_mfma_f32_16x16x32_bf16 v[78:81], v[214:217], v[190:193], v[78:81]
	v_mfma_f32_16x16x32_bf16 v[70:73], v[206:209], v[198:201], v[70:73]
	v_mfma_f32_16x16x32_bf16 v[66:69], v[214:217], v[198:201], v[66:69]
	s_mov_b32 m0, s48
	v_lshl_add_u64 v[148:149], v[220:221], 0, s[10:11]
	s_barrier
	ds_read_b128 v[170:173], v152 offset:49152
	ds_read_b128 v[174:177], v152 offset:50176
	ds_read_b128 v[178:181], v152 offset:51200
	ds_read_b128 v[182:185], v152 offset:52224
	ds_read_b128 v[186:189], v152 offset:53248
	ds_read_b128 v[190:193], v152 offset:54272
	ds_read_b128 v[194:197], v152 offset:55296
	ds_read_b128 v[198:201], v152 offset:56320
	global_load_lds_dwordx4 v[148:149], off
	v_lshl_add_u64 v[148:149], v[222:223], 0, s[10:11]
	s_mov_b32 m0, s49
	s_nop 0
	global_load_lds_dwordx4 v[148:149], off
	s_barrier
	s_waitcnt lgkmcnt(0)
	s_waitcnt lgkmcnt(0)
	v_mfma_f32_16x16x32_bf16 v[62:65], v[154:157], v[170:173], v[62:65]
	v_mfma_f32_16x16x32_bf16 v[58:61], v[162:165], v[170:173], v[58:61]
	v_mfma_f32_16x16x32_bf16 v[54:57], v[154:157], v[178:181], v[54:57]
	v_mfma_f32_16x16x32_bf16 v[46:49], v[162:165], v[178:181], v[46:49]
	v_mfma_f32_16x16x32_bf16 v[38:41], v[154:157], v[186:189], v[38:41]
	v_mfma_f32_16x16x32_bf16 v[30:33], v[162:165], v[186:189], v[30:33]
	v_mfma_f32_16x16x32_bf16 v[22:25], v[154:157], v[194:197], v[22:25]
	v_mfma_f32_16x16x32_bf16 v[14:17], v[162:165], v[194:197], v[14:17]
	v_mfma_f32_16x16x32_bf16 v[62:65], v[158:161], v[174:177], v[62:65]
	v_mfma_f32_16x16x32_bf16 v[58:61], v[166:169], v[174:177], v[58:61]
	v_mfma_f32_16x16x32_bf16 v[54:57], v[158:161], v[182:185], v[54:57]
	v_mfma_f32_16x16x32_bf16 v[46:49], v[166:169], v[182:185], v[46:49]
	v_mfma_f32_16x16x32_bf16 v[38:41], v[158:161], v[190:193], v[38:41]
	v_mfma_f32_16x16x32_bf16 v[30:33], v[166:169], v[190:193], v[30:33]
	v_mfma_f32_16x16x32_bf16 v[22:25], v[158:161], v[198:201], v[22:25]
	v_mfma_f32_16x16x32_bf16 v[14:17], v[166:169], v[198:201], v[14:17]
	s_barrier
	s_add_u32 s42, s42, 0x80080
	s_addc_u32 s43, s43, 0
	s_add_i32 s44, s44, s33
	v_lshl_add_u64 v[148:149], s[42:43], 0, v[132:133]
	s_mov_b32 m0, s44
	s_nop 0
	global_load_lds_dwordx4 v[148:149], off
	v_lshl_add_u64 v[148:149], s[42:43], 0, v[136:137]
	s_add_i32 m0, s44, 0x2000
	s_nop 0
	global_load_lds_dwordx4 v[148:149], off
	s_waitcnt vmcnt(6)
	s_barrier
	v_mfma_f32_16x16x32_bf16 v[50:53], v[202:205], v[170:173], v[50:53]
	v_mfma_f32_16x16x32_bf16 v[42:45], v[210:213], v[170:173], v[42:45]
	v_mfma_f32_16x16x32_bf16 v[34:37], v[202:205], v[178:181], v[34:37]
	v_mfma_f32_16x16x32_bf16 v[26:29], v[210:213], v[178:181], v[26:29]
	v_mfma_f32_16x16x32_bf16 v[18:21], v[202:205], v[186:189], v[18:21]
	v_mfma_f32_16x16x32_bf16 v[10:13], v[210:213], v[186:189], v[10:13]
	v_mfma_f32_16x16x32_bf16 v[6:9], v[202:205], v[194:197], v[6:9]
	v_mfma_f32_16x16x32_bf16 v[2:5], v[210:213], v[194:197], v[2:5]
	v_mfma_f32_16x16x32_bf16 v[50:53], v[206:209], v[174:177], v[50:53]
	v_mfma_f32_16x16x32_bf16 v[42:45], v[214:217], v[174:177], v[42:45]
	v_mfma_f32_16x16x32_bf16 v[34:37], v[206:209], v[182:185], v[34:37]
	v_mfma_f32_16x16x32_bf16 v[26:29], v[214:217], v[182:185], v[26:29]
	v_mfma_f32_16x16x32_bf16 v[18:21], v[206:209], v[190:193], v[18:21]
	v_mfma_f32_16x16x32_bf16 v[10:13], v[214:217], v[190:193], v[10:13]
	v_mfma_f32_16x16x32_bf16 v[6:9], v[206:209], v[198:201], v[6:9]
	v_mfma_f32_16x16x32_bf16 v[2:5], v[214:217], v[198:201], v[2:5]
	s_add_i32 s70, s70, 2
	s_add_u32 s40, s40, 0x100
	s_addc_u32 s41, s41, 0
	s_add_u32 s68, s68, 0x100
	s_addc_u32 s69, s69, 0
	s_cmp_gt_u32 s70, 29
	s_barrier
	s_cbranch_scc0 .LBB0_909
	v_lshl_add_u32 v154, s38, 8, v1
	v_lshl_or_b32 v148, s65, 8, v150
	v_ashrrev_i32_e32 v155, 31, v154
	v_ashrrev_i32_e32 v149, 31, v148
	v_lshlrev_b64 v[156:157], 12, v[154:155]
	v_lshl_add_u64 v[156:157], s[8:9], 0, v[156:157]
	v_lshlrev_b64 v[158:159], 1, v[148:149]
	v_lshl_add_u64 v[148:149], v[156:157], 0, v[158:159]
	v_cvt_pk_bf16_f32 v126, v126, v127
	v_cvt_pk_bf16_f32 v127, v128, v129
	v_cvt_pk_bf16_f32 v128, v122, v123
	v_cvt_pk_bf16_f32 v129, v124, v125
	global_store_dwordx4 v[148:149], v[126:129], off
	v_cvt_pk_bf16_f32 v118, v118, v119
	v_cvt_pk_bf16_f32 v119, v120, v121
	v_cvt_pk_bf16_f32 v120, v110, v111
	v_or_b32_e32 v110, 16, v154
	v_ashrrev_i32_e32 v111, 31, v110
	v_lshlrev_b64 v[110:111], 12, v[110:111]
	v_lshl_add_u64 v[110:111], s[8:9], 0, v[110:111]
	v_cvt_pk_bf16_f32 v121, v112, v113
	global_store_dwordx4 v[148:149], v[118:121], off offset:256
	s_mov_b32 s65, s22
	s_mov_b32 s38, s24
	v_lshl_add_u64 v[118:119], v[110:111], 0, v[158:159]
	v_cvt_pk_bf16_f32 v110, v114, v115
	v_cvt_pk_bf16_f32 v111, v116, v117
	v_cvt_pk_bf16_f32 v112, v106, v107
	v_cvt_pk_bf16_f32 v113, v108, v109
	global_store_dwordx4 v[118:119], v[110:113], off
	v_cvt_pk_bf16_f32 v102, v102, v103
	v_cvt_pk_bf16_f32 v103, v104, v105
	v_cvt_pk_bf16_f32 v104, v94, v95
	v_or_b32_e32 v94, 32, v154
	v_ashrrev_i32_e32 v95, 31, v94
	v_lshlrev_b64 v[94:95], 12, v[94:95]
	v_lshl_add_u64 v[94:95], s[8:9], 0, v[94:95]
	v_cvt_pk_bf16_f32 v105, v96, v97
	global_store_dwordx4 v[118:119], v[102:105], off offset:256
	s_mov_b64 s[42:43], s[36:37]
	s_mov_b64 s[40:41], s[26:27]
	v_lshl_add_u64 v[102:103], v[94:95], 0, v[158:159]
	v_cvt_pk_bf16_f32 v94, v98, v99
	v_cvt_pk_bf16_f32 v95, v100, v101
	v_cvt_pk_bf16_f32 v96, v90, v91
	v_cvt_pk_bf16_f32 v97, v92, v93
	global_store_dwordx4 v[102:103], v[94:97], off
	v_cvt_pk_bf16_f32 v86, v86, v87
	v_cvt_pk_bf16_f32 v87, v88, v89
	v_cvt_pk_bf16_f32 v88, v78, v79
	v_or_b32_e32 v78, 48, v154
	v_ashrrev_i32_e32 v79, 31, v78
	v_lshlrev_b64 v[78:79], 12, v[78:79]
	v_lshl_add_u64 v[78:79], s[8:9], 0, v[78:79]
	v_cvt_pk_bf16_f32 v89, v80, v81
	global_store_dwordx4 v[102:103], v[86:89], off offset:256
	s_nop 1
	v_lshl_add_u64 v[86:87], v[78:79], 0, v[158:159]
	v_cvt_pk_bf16_f32 v78, v82, v83
	v_cvt_pk_bf16_f32 v79, v84, v85
	v_cvt_pk_bf16_f32 v80, v74, v75
	v_cvt_pk_bf16_f32 v81, v76, v77
	global_store_dwordx4 v[86:87], v[78:81], off
	v_cvt_pk_bf16_f32 v70, v70, v71
	v_cvt_pk_bf16_f32 v71, v72, v73
	v_cvt_pk_bf16_f32 v72, v66, v67
	v_cvt_pk_bf16_f32 v73, v68, v69
	global_store_dwordx4 v[86:87], v[70:73], off offset:256
	v_cvt_pk_bf16_f32 v62, v62, v63
	v_cvt_pk_bf16_f32 v63, v64, v65
	v_cvt_pk_bf16_f32 v64, v58, v59
	v_add_co_u32_e32 v58, vcc, s61, v148
	v_lshl_add_u64 v[66:67], v[148:149], 0, s[6:7]
	s_nop 0
	v_addc_co_u32_e32 v59, vcc, 0, v149, vcc
	v_cvt_pk_bf16_f32 v65, v60, v61
	global_store_dwordx4 v[58:59], v[62:65], off
	v_cvt_pk_bf16_f32 v50, v50, v51
	v_cvt_pk_bf16_f32 v51, v52, v53
	v_cvt_pk_bf16_f32 v52, v42, v43
	v_cvt_pk_bf16_f32 v53, v44, v45
	global_store_dwordx4 v[66:67], v[50:53], off offset:256
	v_cvt_pk_bf16_f32 v42, v54, v55
	v_cvt_pk_bf16_f32 v43, v56, v57
	v_cvt_pk_bf16_f32 v44, v46, v47
	v_add_co_u32_e32 v46, vcc, s62, v148
	s_nop 0
	v_lshl_add_u64 v[50:51], v[148:149], 0, s[16:17]
	v_addc_co_u32_e32 v47, vcc, 0, v149, vcc
	v_cvt_pk_bf16_f32 v45, v48, v49
	global_store_dwordx4 v[46:47], v[42:45], off
	v_cvt_pk_bf16_f32 v34, v34, v35
	v_cvt_pk_bf16_f32 v35, v36, v37
	v_cvt_pk_bf16_f32 v36, v26, v27
	v_cvt_pk_bf16_f32 v37, v28, v29
	global_store_dwordx4 v[50:51], v[34:37], off offset:256
	v_cvt_pk_bf16_f32 v26, v38, v39
	v_cvt_pk_bf16_f32 v27, v40, v41
	v_cvt_pk_bf16_f32 v28, v30, v31
	v_add_co_u32_e32 v30, vcc, s63, v148
	s_nop 0
	v_lshl_add_u64 v[34:35], v[148:149], 0, s[18:19]
	v_addc_co_u32_e32 v31, vcc, 0, v149, vcc
	v_cvt_pk_bf16_f32 v29, v32, v33
	global_store_dwordx4 v[30:31], v[26:29], off
	v_cvt_pk_bf16_f32 v18, v18, v19
	v_cvt_pk_bf16_f32 v19, v20, v21
	v_cvt_pk_bf16_f32 v20, v10, v11
	v_cvt_pk_bf16_f32 v21, v12, v13
	global_store_dwordx4 v[34:35], v[18:21], off offset:256
	v_cvt_pk_bf16_f32 v10, v22, v23
	v_cvt_pk_bf16_f32 v11, v24, v25
	v_cvt_pk_bf16_f32 v12, v14, v15
	v_add_co_u32_e32 v14, vcc, s64, v148
	s_nop 0
	v_lshl_add_u64 v[18:19], v[148:149], 0, s[20:21]
	v_addc_co_u32_e32 v15, vcc, 0, v149, vcc
	s_and_b64 vcc, exec, s[0:1]
	v_cvt_pk_bf16_f32 v13, v16, v17
	global_store_dwordx4 v[14:15], v[10:13], off
	v_cvt_pk_bf16_f32 v6, v6, v7
	v_cvt_pk_bf16_f32 v7, v8, v9
	v_cvt_pk_bf16_f32 v8, v2, v3
	v_cvt_pk_bf16_f32 v9, v4, v5
	global_store_dwordx4 v[18:19], v[6:9], off offset:256
	s_cbranch_vccz .LBB0_902
	s_waitcnt vmcnt(0)
	s_cmpk_gt_u32 s3, 0xff
	s_cbranch_scc1 .LBB0_913
	s_barrier
